# gates/merge/out GEMM epilogues rewritten: all chunk loads of a tile issued up front via scalar-stepped row pointers (were 8 serial load-wait-compute-store rounds per tile); gate vector loaded once per
# speedup vs baseline: 1.0365x; 1.0184x over previous
; __device__ void phase_gates(PRef p, int l, const bf16* H2, bf16* sA, bf16* sB) {
;     ...
;     int n = ct >> 2, c0 = (ct & 3) * 128;
;     bf16* dst = n == 0 ? p.HY : (n == 1 ? p.ZB : p.ZC);
;     int ld = n == 2 ? 768 : 512;
;     stage_tile<2>(acc, sA);
;     TILE_CHUNKS(2, sA, {
;       u32x4* pp = (u32x4*)(dst + (size_t)(rt * 128 + trow) * ld + c0 + tcol);
;       u32x4 yv = *pp;
;       u32x4 ov;
;       _Pragma("unroll") for (int j = 0; j < 4; j++) {
;         float g0 = __uint_as_float(cv[j] << 16), g1 = __uint_as_float(cv[j] & 0xffff0000u);
;         g0 = g0 / (1.f + __expf(-g0));
;         g1 = g1 / (1.f + __expf(-g1));
;         float y0 = __uint_as_float(yv[j] << 16), y1 = __uint_as_float(yv[j] & 0xffff0000u);
;         ov[j] = pack2(y0 * g0, y1 * g1);
;       }
;       *pp = ov;
;     })
.LBB0_867:
	s_ashr_i32 s11, s12, 2
	s_cmp_eq_u32 s11, 1
	s_movk_i32 s0, 0x160
	s_cselect_b32 s0, s0, 0x168
	s_cmp_gt_u32 s12, 3
	s_cselect_b32 s0, s0, 0x150
	s_add_u32 s0, s22, s0
	s_addc_u32 s1, s23, 0
	v_mov_b32_e32 v0, v196
	s_load_dwordx2 s[14:15], s[0:1], 0x0
	v_cvt_pk_bf16_f32 v52, v52, v53
	v_lshrrev_b32_e32 v1, 1, v0
	v_and_b32_e32 v2, 31, v0
	v_and_or_b32 v1, v1, s75, v2
	v_and_b32_e32 v2, 64, v0
	v_lshrrev_b32_e32 v0, 2, v0
	v_and_b32_e32 v0, 8, v0
	v_lshl_or_b32 v0, v2, 1, v0
	v_mad_u64_u32 v[0:1], s[0:1], v1, s52, v[0:1]
	v_cvt_pk_bf16_f32 v53, v54, v55
	v_cvt_pk_bf16_f32 v54, v56, v57
	v_cvt_pk_bf16_f32 v55, v58, v59
	v_cvt_pk_bf16_f32 v36, v36, v37
	v_cvt_pk_bf16_f32 v37, v38, v39
	v_cvt_pk_bf16_f32 v38, v40, v41
	v_cvt_pk_bf16_f32 v39, v42, v43
	s_waitcnt lgkmcnt(0)
	s_barrier
	ds_write2_b64 v0, v[52:53], v[54:55] offset1:2
	v_cvt_pk_bf16_f32 v52, v60, v61
	v_cvt_pk_bf16_f32 v53, v62, v63
	v_cvt_pk_bf16_f32 v54, v64, v65
	v_cvt_pk_bf16_f32 v55, v66, v67
	ds_write2_b64 v0, v[36:37], v[38:39] offset0:8 offset1:10
	v_cvt_pk_bf16_f32 v36, v44, v45
	v_cvt_pk_bf16_f32 v37, v46, v47
	v_cvt_pk_bf16_f32 v38, v48, v49
	v_cvt_pk_bf16_f32 v39, v50, v51
	v_cvt_pk_bf16_f32 v20, v20, v21
	v_cvt_pk_bf16_f32 v21, v22, v23
	v_cvt_pk_bf16_f32 v22, v24, v25
	v_cvt_pk_bf16_f32 v23, v26, v27
	v_add_u32_e32 v2, 0x2000, v0
	ds_write2_b64 v0, v[52:53], v[54:55] offset0:4 offset1:6
	ds_write2_b64 v0, v[36:37], v[38:39] offset0:12 offset1:14
	ds_write2_b64 v2, v[20:21], v[22:23] offset0:64 offset1:66
	v_cvt_pk_bf16_f32 v0, v28, v29
	v_cvt_pk_bf16_f32 v1, v30, v31
	v_cvt_pk_bf16_f32 v20, v32, v33
	v_cvt_pk_bf16_f32 v21, v34, v35
	ds_write2_b64 v2, v[0:1], v[20:21] offset0:68 offset1:70
	v_cvt_pk_bf16_f32 v0, v4, v5
	v_cvt_pk_bf16_f32 v1, v6, v7
	v_cvt_pk_bf16_f32 v4, v8, v9
	v_cvt_pk_bf16_f32 v5, v10, v11
	ds_write2_b64 v2, v[0:1], v[4:5] offset0:72 offset1:74
	v_cvt_pk_bf16_f32 v0, v12, v13
	v_cvt_pk_bf16_f32 v1, v14, v15
	v_cvt_pk_bf16_f32 v4, v16, v17
	v_cvt_pk_bf16_f32 v5, v18, v19
	ds_write2_b64 v2, v[0:1], v[4:5] offset0:76 offset1:78
	v_mov_b32_e32 v2, v196
	s_waitcnt lgkmcnt(0)
	s_barrier
	s_cmp_eq_u32 s11, 2
	s_cselect_b32 s13, s83, 0x200
	s_lshl_b32 s0, s12, 8
	s_lshl_b32 s18, s10, 7
	s_and_b32 s0, s0, 0x300
	s_add_u32 s10, s14, s0
	s_addc_u32 s11, s15, 0
	v_lshrrev_b32_e32 v60, 4, v196
	v_and_b32_e32 v61, 15, v196
	v_mul_lo_u32 v62, v60, s52
	v_lshl_add_u32 v62, v61, 4, v62
	v_mul_lo_u32 v63, v60, s13
	v_lshlrev_b32_e32 v63, 1, v63
	v_lshl_add_u32 v63, v61, 4, v63
	s_mul_i32 s0, s18, s13
	s_lshl_b32 s0, s0, 1
	s_add_u32 s98, s10, s0
	s_addc_u32 s99, s11, 0
	s_mov_b64 s[100:101], s[98:99]
	s_lshl_b32 s1, s13, 5
	global_load_dwordx4 v[20:23], v63, s[98:99]
	s_add_u32 s98, s98, s1
	s_addc_u32 s99, s99, 0
	global_load_dwordx4 v[24:27], v63, s[98:99]
	s_add_u32 s98, s98, s1
	s_addc_u32 s99, s99, 0
	global_load_dwordx4 v[28:31], v63, s[98:99]
	s_add_u32 s98, s98, s1
	s_addc_u32 s99, s99, 0
	global_load_dwordx4 v[32:35], v63, s[98:99]
	s_add_u32 s98, s98, s1
	s_addc_u32 s99, s99, 0
	global_load_dwordx4 v[36:39], v63, s[98:99]
	s_add_u32 s98, s98, s1
	s_addc_u32 s99, s99, 0
	global_load_dwordx4 v[40:43], v63, s[98:99]
	s_add_u32 s98, s98, s1
	s_addc_u32 s99, s99, 0
	global_load_dwordx4 v[44:47], v63, s[98:99]
	s_add_u32 s98, s98, s1
	s_addc_u32 s99, s99, 0
	global_load_dwordx4 v[48:51], v63, s[98:99]
	ds_read_b128 v[8:11], v62 offset:0
	s_waitcnt vmcnt(7) lgkmcnt(0)
	v_lshlrev_b32_e32 v12, 16, v8
	v_and_b32_e32 v13, 0xffff0000, v8
	v_lshlrev_b32_e32 v14, 16, v9
	v_and_b32_e32 v15, 0xffff0000, v9
	v_lshlrev_b32_e32 v16, 16, v10
	v_and_b32_e32 v17, 0xffff0000, v10
	v_lshlrev_b32_e32 v18, 16, v11
	v_and_b32_e32 v19, 0xffff0000, v11
	v_mul_f32_e32 v52, 0xbfb8aa3b, v12
	v_mul_f32_e32 v53, 0xbfb8aa3b, v13
	v_mul_f32_e32 v54, 0xbfb8aa3b, v14
	v_mul_f32_e32 v55, 0xbfb8aa3b, v15
	v_mul_f32_e32 v56, 0xbfb8aa3b, v16
	v_mul_f32_e32 v57, 0xbfb8aa3b, v17
	v_mul_f32_e32 v58, 0xbfb8aa3b, v18
	v_mul_f32_e32 v59, 0xbfb8aa3b, v19
	v_exp_f32_e32 v52, v52
	v_exp_f32_e32 v53, v53
	v_exp_f32_e32 v54, v54
	v_exp_f32_e32 v55, v55
	v_exp_f32_e32 v56, v56
	v_exp_f32_e32 v57, v57
	v_exp_f32_e32 v58, v58
	v_exp_f32_e32 v59, v59
	v_add_f32_e32 v52, 1.0, v52
	v_add_f32_e32 v53, 1.0, v53
	v_add_f32_e32 v54, 1.0, v54
	v_add_f32_e32 v55, 1.0, v55
	v_add_f32_e32 v56, 1.0, v56
	v_add_f32_e32 v57, 1.0, v57
	v_add_f32_e32 v58, 1.0, v58
	v_add_f32_e32 v59, 1.0, v59
	v_rcp_f32_e32 v52, v52
	v_rcp_f32_e32 v53, v53
	v_rcp_f32_e32 v54, v54
	v_rcp_f32_e32 v55, v55
	v_rcp_f32_e32 v56, v56
	v_rcp_f32_e32 v57, v57
	v_rcp_f32_e32 v58, v58
	v_rcp_f32_e32 v59, v59
	v_mul_f32_e32 v12, v12, v52
	v_mul_f32_e32 v13, v13, v53
	v_mul_f32_e32 v14, v14, v54
	v_mul_f32_e32 v15, v15, v55
	v_mul_f32_e32 v16, v16, v56
	v_mul_f32_e32 v17, v17, v57
	v_mul_f32_e32 v18, v18, v58
	v_mul_f32_e32 v19, v19, v59
	v_lshlrev_b32_e32 v52, 16, v20
	v_and_b32_e32 v53, 0xffff0000, v20
	v_lshlrev_b32_e32 v54, 16, v21
	v_and_b32_e32 v55, 0xffff0000, v21
	v_lshlrev_b32_e32 v56, 16, v22
	v_and_b32_e32 v57, 0xffff0000, v22
	v_lshlrev_b32_e32 v58, 16, v23
	v_and_b32_e32 v59, 0xffff0000, v23
	v_mul_f32_e32 v12, v12, v52
	v_mul_f32_e32 v13, v13, v53
	v_mul_f32_e32 v14, v14, v54
	v_mul_f32_e32 v15, v15, v55
	v_mul_f32_e32 v16, v16, v56
	v_mul_f32_e32 v17, v17, v57
	v_mul_f32_e32 v18, v18, v58
	v_mul_f32_e32 v19, v19, v59
	v_cvt_pk_bf16_f32 v20, v12, v13
	v_cvt_pk_bf16_f32 v21, v14, v15
	v_cvt_pk_bf16_f32 v22, v16, v17
	v_cvt_pk_bf16_f32 v23, v18, v19
	global_store_dwordx4 v63, v[20:23], s[100:101]
	s_add_u32 s100, s100, s1
	s_addc_u32 s101, s101, 0
	ds_read_b128 v[8:11], v62 offset:4352
	s_waitcnt vmcnt(7) lgkmcnt(0)
; __device__ void phase_gates(PRef p, int l, const bf16* H2, bf16* sA, bf16* sB) {
;     ...
;     TILE_CHUNKS(2, sA, {
;       u32x4* pp = (u32x4*)(dst + (size_t)(rt * 128 + trow) * ld + c0 + tcol);
;       u32x4 yv = *pp;
;       u32x4 ov;
;       _Pragma("unroll") for (int j = 0; j < 4; j++) {
;         float g0 = __uint_as_float(cv[j] << 16), g1 = __uint_as_float(cv[j] & 0xffff0000u);
;         g0 = g0 / (1.f + __expf(-g0));
;         g1 = g1 / (1.f + __expf(-g1));
;         float y0 = __uint_as_float(yv[j] << 16), y1 = __uint_as_float(yv[j] & 0xffff0000u);
;         ov[j] = pack2(y0 * g0, y1 * g1);
;       }
;       *pp = ov;
;     })
	v_lshlrev_b32_e32 v12, 16, v8
	v_and_b32_e32 v13, 0xffff0000, v8
	v_lshlrev_b32_e32 v14, 16, v9
	v_and_b32_e32 v15, 0xffff0000, v9
	v_lshlrev_b32_e32 v16, 16, v10
	v_and_b32_e32 v17, 0xffff0000, v10
	v_lshlrev_b32_e32 v18, 16, v11
	v_and_b32_e32 v19, 0xffff0000, v11
	v_mul_f32_e32 v52, 0xbfb8aa3b, v12
	v_mul_f32_e32 v53, 0xbfb8aa3b, v13
	v_mul_f32_e32 v54, 0xbfb8aa3b, v14
	v_mul_f32_e32 v55, 0xbfb8aa3b, v15
	v_mul_f32_e32 v56, 0xbfb8aa3b, v16
	v_mul_f32_e32 v57, 0xbfb8aa3b, v17
	v_mul_f32_e32 v58, 0xbfb8aa3b, v18
	v_mul_f32_e32 v59, 0xbfb8aa3b, v19
	v_exp_f32_e32 v52, v52
	v_exp_f32_e32 v53, v53
	v_exp_f32_e32 v54, v54
	v_exp_f32_e32 v55, v55
	v_exp_f32_e32 v56, v56
	v_exp_f32_e32 v57, v57
	v_exp_f32_e32 v58, v58
	v_exp_f32_e32 v59, v59
	v_add_f32_e32 v52, 1.0, v52
	v_add_f32_e32 v53, 1.0, v53
	v_add_f32_e32 v54, 1.0, v54
	v_add_f32_e32 v55, 1.0, v55
	v_add_f32_e32 v56, 1.0, v56
	v_add_f32_e32 v57, 1.0, v57
	v_add_f32_e32 v58, 1.0, v58
	v_add_f32_e32 v59, 1.0, v59
	v_rcp_f32_e32 v52, v52
	v_rcp_f32_e32 v53, v53
	v_rcp_f32_e32 v54, v54
	v_rcp_f32_e32 v55, v55
	v_rcp_f32_e32 v56, v56
	v_rcp_f32_e32 v57, v57
	v_rcp_f32_e32 v58, v58
	v_rcp_f32_e32 v59, v59
	v_mul_f32_e32 v12, v12, v52
	v_mul_f32_e32 v13, v13, v53
	v_mul_f32_e32 v14, v14, v54
	v_mul_f32_e32 v15, v15, v55
	v_mul_f32_e32 v16, v16, v56
	v_mul_f32_e32 v17, v17, v57
	v_mul_f32_e32 v18, v18, v58
	v_mul_f32_e32 v19, v19, v59
	v_lshlrev_b32_e32 v52, 16, v24
	v_and_b32_e32 v53, 0xffff0000, v24
	v_lshlrev_b32_e32 v54, 16, v25
	v_and_b32_e32 v55, 0xffff0000, v25
	v_lshlrev_b32_e32 v56, 16, v26
	v_and_b32_e32 v57, 0xffff0000, v26
	v_lshlrev_b32_e32 v58, 16, v27
	v_and_b32_e32 v59, 0xffff0000, v27
	v_mul_f32_e32 v12, v12, v52
	v_mul_f32_e32 v13, v13, v53
	v_mul_f32_e32 v14, v14, v54
	v_mul_f32_e32 v15, v15, v55
	v_mul_f32_e32 v16, v16, v56
	v_mul_f32_e32 v17, v17, v57
	v_mul_f32_e32 v18, v18, v58
	v_mul_f32_e32 v19, v19, v59
	v_cvt_pk_bf16_f32 v24, v12, v13
	v_cvt_pk_bf16_f32 v25, v14, v15
	v_cvt_pk_bf16_f32 v26, v16, v17
	v_cvt_pk_bf16_f32 v27, v18, v19
	global_store_dwordx4 v63, v[24:27], s[100:101]
	s_add_u32 s100, s100, s1
	s_addc_u32 s101, s101, 0
	ds_read_b128 v[8:11], v62 offset:8704
	s_waitcnt vmcnt(7) lgkmcnt(0)
	v_lshlrev_b32_e32 v12, 16, v8
	v_and_b32_e32 v13, 0xffff0000, v8
	v_lshlrev_b32_e32 v14, 16, v9
	v_and_b32_e32 v15, 0xffff0000, v9
	v_lshlrev_b32_e32 v16, 16, v10
	v_and_b32_e32 v17, 0xffff0000, v10
	v_lshlrev_b32_e32 v18, 16, v11
	v_and_b32_e32 v19, 0xffff0000, v11
	v_mul_f32_e32 v52, 0xbfb8aa3b, v12
	v_mul_f32_e32 v53, 0xbfb8aa3b, v13
	v_mul_f32_e32 v54, 0xbfb8aa3b, v14
	v_mul_f32_e32 v55, 0xbfb8aa3b, v15
	v_mul_f32_e32 v56, 0xbfb8aa3b, v16
	v_mul_f32_e32 v57, 0xbfb8aa3b, v17
	v_mul_f32_e32 v58, 0xbfb8aa3b, v18
	v_mul_f32_e32 v59, 0xbfb8aa3b, v19
	v_exp_f32_e32 v52, v52
	v_exp_f32_e32 v53, v53
	v_exp_f32_e32 v54, v54
	v_exp_f32_e32 v55, v55
	v_exp_f32_e32 v56, v56
	v_exp_f32_e32 v57, v57
	v_exp_f32_e32 v58, v58
	v_exp_f32_e32 v59, v59
	v_add_f32_e32 v52, 1.0, v52
	v_add_f32_e32 v53, 1.0, v53
	v_add_f32_e32 v54, 1.0, v54
	v_add_f32_e32 v55, 1.0, v55
	v_add_f32_e32 v56, 1.0, v56
	v_add_f32_e32 v57, 1.0, v57
	v_add_f32_e32 v58, 1.0, v58
	v_add_f32_e32 v59, 1.0, v59
	v_rcp_f32_e32 v52, v52
	v_rcp_f32_e32 v53, v53
	v_rcp_f32_e32 v54, v54
	v_rcp_f32_e32 v55, v55
	v_rcp_f32_e32 v56, v56
	v_rcp_f32_e32 v57, v57
	v_rcp_f32_e32 v58, v58
	v_rcp_f32_e32 v59, v59
	v_mul_f32_e32 v12, v12, v52
	v_mul_f32_e32 v13, v13, v53
	v_mul_f32_e32 v14, v14, v54
	v_mul_f32_e32 v15, v15, v55
	v_mul_f32_e32 v16, v16, v56
	v_mul_f32_e32 v17, v17, v57
	v_mul_f32_e32 v18, v18, v58
	v_mul_f32_e32 v19, v19, v59
	v_lshlrev_b32_e32 v52, 16, v28
	v_and_b32_e32 v53, 0xffff0000, v28
	v_lshlrev_b32_e32 v54, 16, v29
	v_and_b32_e32 v55, 0xffff0000, v29
	v_lshlrev_b32_e32 v56, 16, v30
	v_and_b32_e32 v57, 0xffff0000, v30
	v_lshlrev_b32_e32 v58, 16, v31
	v_and_b32_e32 v59, 0xffff0000, v31
	v_mul_f32_e32 v12, v12, v52
	v_mul_f32_e32 v13, v13, v53
	v_mul_f32_e32 v14, v14, v54
	v_mul_f32_e32 v15, v15, v55
	v_mul_f32_e32 v16, v16, v56
	v_mul_f32_e32 v17, v17, v57
	v_mul_f32_e32 v18, v18, v58
	v_mul_f32_e32 v19, v19, v59
	v_cvt_pk_bf16_f32 v28, v12, v13
	v_cvt_pk_bf16_f32 v29, v14, v15
	v_cvt_pk_bf16_f32 v30, v16, v17
	v_cvt_pk_bf16_f32 v31, v18, v19
	global_store_dwordx4 v63, v[28:31], s[100:101]
	s_add_u32 s100, s100, s1
	s_addc_u32 s101, s101, 0
	ds_read_b128 v[8:11], v62 offset:13056
	s_waitcnt vmcnt(7) lgkmcnt(0)
	v_lshlrev_b32_e32 v12, 16, v8
	v_and_b32_e32 v13, 0xffff0000, v8
	v_lshlrev_b32_e32 v14, 16, v9
	v_and_b32_e32 v15, 0xffff0000, v9
	v_lshlrev_b32_e32 v16, 16, v10
	v_and_b32_e32 v17, 0xffff0000, v10
	v_lshlrev_b32_e32 v18, 16, v11
	v_and_b32_e32 v19, 0xffff0000, v11
	v_mul_f32_e32 v52, 0xbfb8aa3b, v12
	v_mul_f32_e32 v53, 0xbfb8aa3b, v13
	v_mul_f32_e32 v54, 0xbfb8aa3b, v14
	v_mul_f32_e32 v55, 0xbfb8aa3b, v15
	v_mul_f32_e32 v56, 0xbfb8aa3b, v16
	v_mul_f32_e32 v57, 0xbfb8aa3b, v17
	v_mul_f32_e32 v58, 0xbfb8aa3b, v18
	v_mul_f32_e32 v59, 0xbfb8aa3b, v19
	v_exp_f32_e32 v52, v52
	v_exp_f32_e32 v53, v53
	v_exp_f32_e32 v54, v54
	v_exp_f32_e32 v55, v55
	v_exp_f32_e32 v56, v56
	v_exp_f32_e32 v57, v57
	v_exp_f32_e32 v58, v58
	v_exp_f32_e32 v59, v59
	v_add_f32_e32 v52, 1.0, v52
	v_add_f32_e32 v53, 1.0, v53
	v_add_f32_e32 v54, 1.0, v54
	v_add_f32_e32 v55, 1.0, v55
	v_add_f32_e32 v56, 1.0, v56
	v_add_f32_e32 v57, 1.0, v57
	v_add_f32_e32 v58, 1.0, v58
	v_add_f32_e32 v59, 1.0, v59
	v_rcp_f32_e32 v52, v52
	v_rcp_f32_e32 v53, v53
	v_rcp_f32_e32 v54, v54
	v_rcp_f32_e32 v55, v55
	v_rcp_f32_e32 v56, v56
	v_rcp_f32_e32 v57, v57
	v_rcp_f32_e32 v58, v58
	v_rcp_f32_e32 v59, v59
	v_mul_f32_e32 v12, v12, v52
	v_mul_f32_e32 v13, v13, v53
	v_mul_f32_e32 v14, v14, v54
	v_mul_f32_e32 v15, v15, v55
	v_mul_f32_e32 v16, v16, v56
	v_mul_f32_e32 v17, v17, v57
	v_mul_f32_e32 v18, v18, v58
	v_mul_f32_e32 v19, v19, v59
	v_lshlrev_b32_e32 v52, 16, v32
	v_and_b32_e32 v53, 0xffff0000, v32
	v_lshlrev_b32_e32 v54, 16, v33
	v_and_b32_e32 v55, 0xffff0000, v33
	v_lshlrev_b32_e32 v56, 16, v34
	v_and_b32_e32 v57, 0xffff0000, v34
	v_lshlrev_b32_e32 v58, 16, v35
	v_and_b32_e32 v59, 0xffff0000, v35
	v_mul_f32_e32 v12, v12, v52
	v_mul_f32_e32 v13, v13, v53
	v_mul_f32_e32 v14, v14, v54
	v_mul_f32_e32 v15, v15, v55
	v_mul_f32_e32 v16, v16, v56
	v_mul_f32_e32 v17, v17, v57
	v_mul_f32_e32 v18, v18, v58
	v_mul_f32_e32 v19, v19, v59
	v_cvt_pk_bf16_f32 v32, v12, v13
	v_cvt_pk_bf16_f32 v33, v14, v15
	v_cvt_pk_bf16_f32 v34, v16, v17
	v_cvt_pk_bf16_f32 v35, v18, v19
	global_store_dwordx4 v63, v[32:35], s[100:101]
	s_add_u32 s100, s100, s1
	s_addc_u32 s101, s101, 0
	ds_read_b128 v[8:11], v62 offset:17408
	s_waitcnt vmcnt(7) lgkmcnt(0)
; __device__ void phase_gates(PRef p, int l, const bf16* H2, bf16* sA, bf16* sB) {
;     ...
;     TILE_CHUNKS(2, sA, {
;       u32x4* pp = (u32x4*)(dst + (size_t)(rt * 128 + trow) * ld + c0 + tcol);
;       u32x4 yv = *pp;
;       u32x4 ov;
;       _Pragma("unroll") for (int j = 0; j < 4; j++) {
;         float g0 = __uint_as_float(cv[j] << 16), g1 = __uint_as_float(cv[j] & 0xffff0000u);
;         g0 = g0 / (1.f + __expf(-g0));
;         g1 = g1 / (1.f + __expf(-g1));
;         float y0 = __uint_as_float(yv[j] << 16), y1 = __uint_as_float(yv[j] & 0xffff0000u);
;         ov[j] = pack2(y0 * g0, y1 * g1);
;       }
;       *pp = ov;
;     })
	v_lshlrev_b32_e32 v12, 16, v8
	v_and_b32_e32 v13, 0xffff0000, v8
	v_lshlrev_b32_e32 v14, 16, v9
	v_and_b32_e32 v15, 0xffff0000, v9
	v_lshlrev_b32_e32 v16, 16, v10
	v_and_b32_e32 v17, 0xffff0000, v10
	v_lshlrev_b32_e32 v18, 16, v11
	v_and_b32_e32 v19, 0xffff0000, v11
	v_mul_f32_e32 v52, 0xbfb8aa3b, v12
	v_mul_f32_e32 v53, 0xbfb8aa3b, v13
	v_mul_f32_e32 v54, 0xbfb8aa3b, v14
	v_mul_f32_e32 v55, 0xbfb8aa3b, v15
	v_mul_f32_e32 v56, 0xbfb8aa3b, v16
	v_mul_f32_e32 v57, 0xbfb8aa3b, v17
	v_mul_f32_e32 v58, 0xbfb8aa3b, v18
	v_mul_f32_e32 v59, 0xbfb8aa3b, v19
	v_exp_f32_e32 v52, v52
	v_exp_f32_e32 v53, v53
	v_exp_f32_e32 v54, v54
	v_exp_f32_e32 v55, v55
	v_exp_f32_e32 v56, v56
	v_exp_f32_e32 v57, v57
	v_exp_f32_e32 v58, v58
	v_exp_f32_e32 v59, v59
	v_add_f32_e32 v52, 1.0, v52
	v_add_f32_e32 v53, 1.0, v53
	v_add_f32_e32 v54, 1.0, v54
	v_add_f32_e32 v55, 1.0, v55
	v_add_f32_e32 v56, 1.0, v56
	v_add_f32_e32 v57, 1.0, v57
	v_add_f32_e32 v58, 1.0, v58
	v_add_f32_e32 v59, 1.0, v59
	v_rcp_f32_e32 v52, v52
	v_rcp_f32_e32 v53, v53
	v_rcp_f32_e32 v54, v54
	v_rcp_f32_e32 v55, v55
	v_rcp_f32_e32 v56, v56
	v_rcp_f32_e32 v57, v57
	v_rcp_f32_e32 v58, v58
	v_rcp_f32_e32 v59, v59
	v_mul_f32_e32 v12, v12, v52
	v_mul_f32_e32 v13, v13, v53
	v_mul_f32_e32 v14, v14, v54
	v_mul_f32_e32 v15, v15, v55
	v_mul_f32_e32 v16, v16, v56
	v_mul_f32_e32 v17, v17, v57
	v_mul_f32_e32 v18, v18, v58
	v_mul_f32_e32 v19, v19, v59
	v_lshlrev_b32_e32 v52, 16, v36
	v_and_b32_e32 v53, 0xffff0000, v36
	v_lshlrev_b32_e32 v54, 16, v37
	v_and_b32_e32 v55, 0xffff0000, v37
	v_lshlrev_b32_e32 v56, 16, v38
	v_and_b32_e32 v57, 0xffff0000, v38
	v_lshlrev_b32_e32 v58, 16, v39
	v_and_b32_e32 v59, 0xffff0000, v39
	v_mul_f32_e32 v12, v12, v52
	v_mul_f32_e32 v13, v13, v53
	v_mul_f32_e32 v14, v14, v54
	v_mul_f32_e32 v15, v15, v55
	v_mul_f32_e32 v16, v16, v56
	v_mul_f32_e32 v17, v17, v57
	v_mul_f32_e32 v18, v18, v58
	v_mul_f32_e32 v19, v19, v59
	v_cvt_pk_bf16_f32 v36, v12, v13
	v_cvt_pk_bf16_f32 v37, v14, v15
	v_cvt_pk_bf16_f32 v38, v16, v17
	v_cvt_pk_bf16_f32 v39, v18, v19
	global_store_dwordx4 v63, v[36:39], s[100:101]
	s_add_u32 s100, s100, s1
	s_addc_u32 s101, s101, 0
	ds_read_b128 v[8:11], v62 offset:21760
	s_waitcnt vmcnt(7) lgkmcnt(0)
	v_lshlrev_b32_e32 v12, 16, v8
	v_and_b32_e32 v13, 0xffff0000, v8
	v_lshlrev_b32_e32 v14, 16, v9
	v_and_b32_e32 v15, 0xffff0000, v9
	v_lshlrev_b32_e32 v16, 16, v10
	v_and_b32_e32 v17, 0xffff0000, v10
	v_lshlrev_b32_e32 v18, 16, v11
	v_and_b32_e32 v19, 0xffff0000, v11
	v_mul_f32_e32 v52, 0xbfb8aa3b, v12
	v_mul_f32_e32 v53, 0xbfb8aa3b, v13
	v_mul_f32_e32 v54, 0xbfb8aa3b, v14
	v_mul_f32_e32 v55, 0xbfb8aa3b, v15
	v_mul_f32_e32 v56, 0xbfb8aa3b, v16
	v_mul_f32_e32 v57, 0xbfb8aa3b, v17
	v_mul_f32_e32 v58, 0xbfb8aa3b, v18
	v_mul_f32_e32 v59, 0xbfb8aa3b, v19
	v_exp_f32_e32 v52, v52
	v_exp_f32_e32 v53, v53
	v_exp_f32_e32 v54, v54
	v_exp_f32_e32 v55, v55
	v_exp_f32_e32 v56, v56
	v_exp_f32_e32 v57, v57
	v_exp_f32_e32 v58, v58
	v_exp_f32_e32 v59, v59
	v_add_f32_e32 v52, 1.0, v52
	v_add_f32_e32 v53, 1.0, v53
	v_add_f32_e32 v54, 1.0, v54
	v_add_f32_e32 v55, 1.0, v55
	v_add_f32_e32 v56, 1.0, v56
	v_add_f32_e32 v57, 1.0, v57
	v_add_f32_e32 v58, 1.0, v58
	v_add_f32_e32 v59, 1.0, v59
	v_rcp_f32_e32 v52, v52
	v_rcp_f32_e32 v53, v53
	v_rcp_f32_e32 v54, v54
	v_rcp_f32_e32 v55, v55
	v_rcp_f32_e32 v56, v56
	v_rcp_f32_e32 v57, v57
	v_rcp_f32_e32 v58, v58
	v_rcp_f32_e32 v59, v59
	v_mul_f32_e32 v12, v12, v52
	v_mul_f32_e32 v13, v13, v53
	v_mul_f32_e32 v14, v14, v54
	v_mul_f32_e32 v15, v15, v55
	v_mul_f32_e32 v16, v16, v56
	v_mul_f32_e32 v17, v17, v57
	v_mul_f32_e32 v18, v18, v58
	v_mul_f32_e32 v19, v19, v59
	v_lshlrev_b32_e32 v52, 16, v40
	v_and_b32_e32 v53, 0xffff0000, v40
	v_lshlrev_b32_e32 v54, 16, v41
	v_and_b32_e32 v55, 0xffff0000, v41
	v_lshlrev_b32_e32 v56, 16, v42
	v_and_b32_e32 v57, 0xffff0000, v42
	v_lshlrev_b32_e32 v58, 16, v43
	v_and_b32_e32 v59, 0xffff0000, v43
	v_mul_f32_e32 v12, v12, v52
	v_mul_f32_e32 v13, v13, v53
	v_mul_f32_e32 v14, v14, v54
	v_mul_f32_e32 v15, v15, v55
	v_mul_f32_e32 v16, v16, v56
	v_mul_f32_e32 v17, v17, v57
	v_mul_f32_e32 v18, v18, v58
	v_mul_f32_e32 v19, v19, v59
	v_cvt_pk_bf16_f32 v40, v12, v13
	v_cvt_pk_bf16_f32 v41, v14, v15
	v_cvt_pk_bf16_f32 v42, v16, v17
	v_cvt_pk_bf16_f32 v43, v18, v19
	global_store_dwordx4 v63, v[40:43], s[100:101]
	s_add_u32 s100, s100, s1
	s_addc_u32 s101, s101, 0
	ds_read_b128 v[8:11], v62 offset:26112
	s_waitcnt vmcnt(7) lgkmcnt(0)
; __device__ void phase_gates(PRef p, int l, const bf16* H2, bf16* sA, bf16* sB) {
;     ...
;     TILE_CHUNKS(2, sA, {
;       u32x4* pp = (u32x4*)(dst + (size_t)(rt * 128 + trow) * ld + c0 + tcol);
;       u32x4 yv = *pp;
;       u32x4 ov;
;       _Pragma("unroll") for (int j = 0; j < 4; j++) {
;         float g0 = __uint_as_float(cv[j] << 16), g1 = __uint_as_float(cv[j] & 0xffff0000u);
;         g0 = g0 / (1.f + __expf(-g0));
;         g1 = g1 / (1.f + __expf(-g1));
;         float y0 = __uint_as_float(yv[j] << 16), y1 = __uint_as_float(yv[j] & 0xffff0000u);
;         ov[j] = pack2(y0 * g0, y1 * g1);
;       }
;       *pp = ov;
;     })
	v_lshlrev_b32_e32 v12, 16, v8
	v_and_b32_e32 v13, 0xffff0000, v8
	v_lshlrev_b32_e32 v14, 16, v9
	v_and_b32_e32 v15, 0xffff0000, v9
	v_lshlrev_b32_e32 v16, 16, v10
	v_and_b32_e32 v17, 0xffff0000, v10
	v_lshlrev_b32_e32 v18, 16, v11
	v_and_b32_e32 v19, 0xffff0000, v11
	v_mul_f32_e32 v52, 0xbfb8aa3b, v12
	v_mul_f32_e32 v53, 0xbfb8aa3b, v13
	v_mul_f32_e32 v54, 0xbfb8aa3b, v14
	v_mul_f32_e32 v55, 0xbfb8aa3b, v15
	v_mul_f32_e32 v56, 0xbfb8aa3b, v16
	v_mul_f32_e32 v57, 0xbfb8aa3b, v17
	v_mul_f32_e32 v58, 0xbfb8aa3b, v18
	v_mul_f32_e32 v59, 0xbfb8aa3b, v19
	v_exp_f32_e32 v52, v52
	v_exp_f32_e32 v53, v53
	v_exp_f32_e32 v54, v54
	v_exp_f32_e32 v55, v55
	v_exp_f32_e32 v56, v56
	v_exp_f32_e32 v57, v57
	v_exp_f32_e32 v58, v58
	v_exp_f32_e32 v59, v59
	v_add_f32_e32 v52, 1.0, v52
	v_add_f32_e32 v53, 1.0, v53
	v_add_f32_e32 v54, 1.0, v54
	v_add_f32_e32 v55, 1.0, v55
	v_add_f32_e32 v56, 1.0, v56
	v_add_f32_e32 v57, 1.0, v57
	v_add_f32_e32 v58, 1.0, v58
	v_add_f32_e32 v59, 1.0, v59
	v_rcp_f32_e32 v52, v52
	v_rcp_f32_e32 v53, v53
	v_rcp_f32_e32 v54, v54
	v_rcp_f32_e32 v55, v55
	v_rcp_f32_e32 v56, v56
	v_rcp_f32_e32 v57, v57
	v_rcp_f32_e32 v58, v58
	v_rcp_f32_e32 v59, v59
	v_mul_f32_e32 v12, v12, v52
	v_mul_f32_e32 v13, v13, v53
	v_mul_f32_e32 v14, v14, v54
	v_mul_f32_e32 v15, v15, v55
	v_mul_f32_e32 v16, v16, v56
	v_mul_f32_e32 v17, v17, v57
	v_mul_f32_e32 v18, v18, v58
	v_mul_f32_e32 v19, v19, v59
	v_lshlrev_b32_e32 v52, 16, v44
	v_and_b32_e32 v53, 0xffff0000, v44
	v_lshlrev_b32_e32 v54, 16, v45
	v_and_b32_e32 v55, 0xffff0000, v45
	v_lshlrev_b32_e32 v56, 16, v46
	v_and_b32_e32 v57, 0xffff0000, v46
	v_lshlrev_b32_e32 v58, 16, v47
	v_and_b32_e32 v59, 0xffff0000, v47
	v_mul_f32_e32 v12, v12, v52
	v_mul_f32_e32 v13, v13, v53
	v_mul_f32_e32 v14, v14, v54
	v_mul_f32_e32 v15, v15, v55
	v_mul_f32_e32 v16, v16, v56
	v_mul_f32_e32 v17, v17, v57
	v_mul_f32_e32 v18, v18, v58
	v_mul_f32_e32 v19, v19, v59
	v_cvt_pk_bf16_f32 v44, v12, v13
	v_cvt_pk_bf16_f32 v45, v14, v15
	v_cvt_pk_bf16_f32 v46, v16, v17
	v_cvt_pk_bf16_f32 v47, v18, v19
	global_store_dwordx4 v63, v[44:47], s[100:101]
	s_add_u32 s100, s100, s1
	s_addc_u32 s101, s101, 0
	ds_read_b128 v[8:11], v62 offset:30464
	s_waitcnt vmcnt(7) lgkmcnt(0)
	v_lshlrev_b32_e32 v12, 16, v8
	v_and_b32_e32 v13, 0xffff0000, v8
	v_lshlrev_b32_e32 v14, 16, v9
	v_and_b32_e32 v15, 0xffff0000, v9
	v_lshlrev_b32_e32 v16, 16, v10
	v_and_b32_e32 v17, 0xffff0000, v10
	v_lshlrev_b32_e32 v18, 16, v11
	v_and_b32_e32 v19, 0xffff0000, v11
	v_mul_f32_e32 v52, 0xbfb8aa3b, v12
	v_mul_f32_e32 v53, 0xbfb8aa3b, v13
	v_mul_f32_e32 v54, 0xbfb8aa3b, v14
	v_mul_f32_e32 v55, 0xbfb8aa3b, v15
	v_mul_f32_e32 v56, 0xbfb8aa3b, v16
	v_mul_f32_e32 v57, 0xbfb8aa3b, v17
	v_mul_f32_e32 v58, 0xbfb8aa3b, v18
	v_mul_f32_e32 v59, 0xbfb8aa3b, v19
	v_exp_f32_e32 v52, v52
	v_exp_f32_e32 v53, v53
	v_exp_f32_e32 v54, v54
	v_exp_f32_e32 v55, v55
	v_exp_f32_e32 v56, v56
	v_exp_f32_e32 v57, v57
	v_exp_f32_e32 v58, v58
	v_exp_f32_e32 v59, v59
	v_add_f32_e32 v52, 1.0, v52
	v_add_f32_e32 v53, 1.0, v53
	v_add_f32_e32 v54, 1.0, v54
	v_add_f32_e32 v55, 1.0, v55
	v_add_f32_e32 v56, 1.0, v56
	v_add_f32_e32 v57, 1.0, v57
	v_add_f32_e32 v58, 1.0, v58
	v_add_f32_e32 v59, 1.0, v59
	v_rcp_f32_e32 v52, v52
	v_rcp_f32_e32 v53, v53
	v_rcp_f32_e32 v54, v54
	v_rcp_f32_e32 v55, v55
	v_rcp_f32_e32 v56, v56
	v_rcp_f32_e32 v57, v57
	v_rcp_f32_e32 v58, v58
	v_rcp_f32_e32 v59, v59
	v_mul_f32_e32 v12, v12, v52
	v_mul_f32_e32 v13, v13, v53
	v_mul_f32_e32 v14, v14, v54
	v_mul_f32_e32 v15, v15, v55
	v_mul_f32_e32 v16, v16, v56
	v_mul_f32_e32 v17, v17, v57
	v_mul_f32_e32 v18, v18, v58
	v_mul_f32_e32 v19, v19, v59
	v_lshlrev_b32_e32 v52, 16, v48
	v_and_b32_e32 v53, 0xffff0000, v48
	v_lshlrev_b32_e32 v54, 16, v49
	v_and_b32_e32 v55, 0xffff0000, v49
	v_lshlrev_b32_e32 v56, 16, v50
	v_and_b32_e32 v57, 0xffff0000, v50
	v_lshlrev_b32_e32 v58, 16, v51
	v_and_b32_e32 v59, 0xffff0000, v51
	v_mul_f32_e32 v12, v12, v52
	v_mul_f32_e32 v13, v13, v53
	v_mul_f32_e32 v14, v14, v54
	v_mul_f32_e32 v15, v15, v55
	v_mul_f32_e32 v16, v16, v56
	v_mul_f32_e32 v17, v17, v57
	v_mul_f32_e32 v18, v18, v58
	v_mul_f32_e32 v19, v19, v59
	v_cvt_pk_bf16_f32 v48, v12, v13
	v_cvt_pk_bf16_f32 v49, v14, v15
	v_cvt_pk_bf16_f32 v50, v16, v17
	v_cvt_pk_bf16_f32 v51, v18, v19
	global_store_dwordx4 v63, v[48:51], s[100:101]

; __device__ void phase_merge(PRef p, int l, const bf16* H2, bf16* M, bf16* sA, bf16* sB) {
;     ...
;     for (int n = 0; n < 3; n++) {
;       const bf16* U = n == 0 ? p.HY : (n == 1 ? p.ZB : p.ZC);
;       int ldu = n == 2 ? 768 : 512;
;       uint32_t gp[2][2][8];
;       {
;         f32x16 a2[2][2];
;         zero_acc<2>(a2);
;         gemm_tile<2>(a2, H2 + (size_t)rt * 128 * 1024, 1024, p.WT3 + ((size_t)n * 1024 + ct * 128) * 1024, 1024, 1024, sA, sB);
.LBB0_956:
	s_add_i32 s95, s95, 1
	s_add_u32 s24, s24, 0x200000
	s_addc_u32 s25, s25, 0
	s_add_u32 s26, s26, 0x200000
	s_addc_u32 s27, s27, 0
	s_add_u32 s36, s36, 0x200000
	s_addc_u32 s37, s37, 0
	s_add_u32 s38, s38, 0x200000
	s_addc_u32 s39, s39, 0
	s_add_u32 s40, s40, 0x200000
	s_addc_u32 s41, s41, 0
	s_add_u32 s42, s42, 0x200000
	s_addc_u32 s43, s43, 0
	s_add_u32 s44, s44, 0x100000
	s_addc_u32 s45, s45, 0
	s_add_u32 s46, s46, 0x100000
	s_addc_u32 s47, s47, 0
	s_add_u32 s48, s48, 0x100000
	s_addc_u32 s49, s49, 0
	s_add_u32 s50, s50, 0x100000
	s_addc_u32 s51, s51, 0
	s_add_u32 s78, s78, 0x100000
	s_addc_u32 s79, s79, 0
	s_add_u32 s80, s80, 0x100000
	s_addc_u32 s81, s81, 0
	s_add_u32 s86, s86, 0x100000
	s_addc_u32 s87, s87, 0
	s_cmp_lg_u32 s95, 3
	s_cbranch_scc0 .LBB0_951

; __device__ void phase_merge(PRef p, int l, const bf16* H2, bf16* M, bf16* sA, bf16* sB) {
;     ...
; #pragma unroll
;         for (int a = 0; a < 2; a++)
; #pragma unroll
;           for (int bb = 0; bb < 2; bb++)
; #pragma unroll
;             for (int r = 0; r < 8; r++) {
;               float g0 = __fdividef(1.f, 1.f + __expf(-a2[a][bb][2 * r]));
;               float g1 = __fdividef(1.f, 1.f + __expf(-a2[a][bb][2 * r + 1]));
;               gp[a][bb][r] = pack2(g0, g1);
;             }
.LBB0_972:
	v_mul_f32_e32 v0, 0xbfb8aa3b, v116
	v_mul_f32_e32 v1, 0xbfb8aa3b, v117
	v_exp_f32_e32 v0, v0
	v_exp_f32_e32 v1, v1
	v_mul_f32_e32 v100, 0xbfb8aa3b, v100
	v_mul_f32_e32 v101, 0xbfb8aa3b, v101
	v_exp_f32_e32 v100, v100
	v_pk_add_f32 v[0:1], v[0:1], 1.0 op_sel_hi:[1,0]
	v_exp_f32_e32 v101, v101
	v_div_scale_f32 v2, s[0:1], v1, v1, 1.0
	v_rcp_f32_e32 v116, v2
	v_pk_add_f32 v[100:101], v[100:101], 1.0 op_sel_hi:[1,0]
	v_mul_f32_e32 v68, 0xbfb8aa3b, v68
	v_mul_f32_e32 v69, 0xbfb8aa3b, v69
	v_fma_f32 v117, -v2, v116, 1.0
	v_fmac_f32_e32 v116, v117, v116
	v_div_scale_f32 v117, vcc, 1.0, v1, 1.0
	v_mul_f32_e32 v133, v117, v116
	s_waitcnt vmcnt(6)
	v_fma_f32 v134, -v2, v133, v117
	v_fmac_f32_e32 v133, v134, v116
	v_fma_f32 v2, -v2, v133, v117
	v_div_fmas_f32 v2, v2, v116, v133
	v_div_fixup_f32 v1, v2, v1, 1.0
	v_div_scale_f32 v2, s[0:1], v0, v0, 1.0
	v_rcp_f32_e32 v116, v2
	v_exp_f32_e32 v68, v68
	v_exp_f32_e32 v69, v69
	v_mul_f32_e32 v4, 0xbfb8aa3b, v4
	v_fma_f32 v117, -v2, v116, 1.0
	v_fmac_f32_e32 v116, v117, v116
	v_div_scale_f32 v117, vcc, 1.0, v0, 1.0
	v_mul_f32_e32 v133, v117, v116
	v_fma_f32 v134, -v2, v133, v117
	v_fmac_f32_e32 v133, v134, v116
	v_fma_f32 v2, -v2, v133, v117
	v_div_fmas_f32 v2, v2, v116, v133
	v_div_fixup_f32 v0, v2, v0, 1.0
	v_cvt_pk_bf16_f32 v0, v0, v1
	v_mul_f32_e32 v1, 0xbfb8aa3b, v118
	v_exp_f32_e32 v116, v1
	v_mul_f32_e32 v1, 0xbfb8aa3b, v119
	v_exp_f32_e32 v117, v1
	v_pk_add_f32 v[68:69], v[68:69], 1.0 op_sel_hi:[1,0]
	v_mul_f32_e32 v5, 0xbfb8aa3b, v5
	v_exp_f32_e32 v4, v4
	v_pk_add_f32 v[116:117], v[116:117], 1.0 op_sel_hi:[1,0]
	v_exp_f32_e32 v5, v5
	v_div_scale_f32 v1, s[0:1], v117, v117, 1.0
	v_rcp_f32_e32 v2, v1
	v_pk_add_f32 v[4:5], v[4:5], 1.0 op_sel_hi:[1,0]
	s_cmp_lg_u32 s95, 0
	s_cselect_b64 s[54:55], -1, 0
	v_fma_f32 v118, -v1, v2, 1.0
	v_fmac_f32_e32 v2, v118, v2
	v_div_scale_f32 v118, vcc, 1.0, v117, 1.0
	v_mul_f32_e32 v119, v118, v2
	v_fma_f32 v133, -v1, v119, v118
	v_fmac_f32_e32 v119, v133, v2
	v_fma_f32 v1, -v1, v119, v118
	v_div_fmas_f32 v1, v1, v2, v119
	v_div_scale_f32 v2, s[0:1], v116, v116, 1.0
	v_div_fixup_f32 v1, v1, v117, 1.0
	v_rcp_f32_e32 v117, v2
	s_nop 0
	v_fma_f32 v118, -v2, v117, 1.0
	v_fmac_f32_e32 v117, v118, v117
	v_div_scale_f32 v118, vcc, 1.0, v116, 1.0
	v_mul_f32_e32 v119, v118, v117
	v_fma_f32 v133, -v2, v119, v118
	v_fmac_f32_e32 v119, v133, v117
	v_fma_f32 v2, -v2, v119, v118
	v_div_fmas_f32 v2, v2, v117, v119
	v_div_fixup_f32 v2, v2, v116, 1.0
	v_cvt_pk_bf16_f32 v1, v2, v1
	v_mul_f32_e32 v2, 0xbfb8aa3b, v120
	v_exp_f32_e32 v116, v2
	v_mul_f32_e32 v2, 0xbfb8aa3b, v121
	v_exp_f32_e32 v117, v2
	s_nop 0
	v_pk_add_f32 v[116:117], v[116:117], 1.0 op_sel_hi:[1,0]
	s_nop 0
	v_rcp_f32_e32 v118, v117
	s_nop 0
	v_mul_f32_e32 v2, 1.0, v118
	v_rcp_f32_e32 v118, v116
	s_nop 0
	v_mul_f32_e32 v116, 1.0, v118
	v_cvt_pk_bf16_f32 v2, v116, v2
	v_mul_f32_e32 v116, 0xbfb8aa3b, v122
	v_mul_f32_e32 v117, 0xbfb8aa3b, v123
	v_exp_f32_e32 v116, v116
	v_exp_f32_e32 v117, v117
	s_nop 0
	v_pk_add_f32 v[116:117], v[116:117], 1.0 op_sel_hi:[1,0]
	s_nop 0
	v_rcp_f32_e32 v119, v117
	s_nop 0
	v_mul_f32_e32 v117, 1.0, v119
	v_rcp_f32_e32 v119, v116
	s_nop 0
	v_mul_f32_e32 v116, 1.0, v119
	v_cvt_pk_bf16_f32 v116, v116, v117
	v_mul_f32_e32 v117, 0xbfb8aa3b, v124
	v_exp_f32_e32 v118, v117
	v_mul_f32_e32 v117, 0xbfb8aa3b, v125
	v_exp_f32_e32 v119, v117
	s_nop 0
	v_pk_add_f32 v[118:119], v[118:119], 1.0 op_sel_hi:[1,0]
	s_nop 0
	v_rcp_f32_e32 v120, v119
	s_nop 0
	v_mul_f32_e32 v117, 1.0, v120
	v_rcp_f32_e32 v120, v118
	s_nop 0
	v_mul_f32_e32 v118, 1.0, v120
	v_cvt_pk_bf16_f32 v117, v118, v117
	v_mul_f32_e32 v118, 0xbfb8aa3b, v126
	v_mul_f32_e32 v119, 0xbfb8aa3b, v127
	v_exp_f32_e32 v118, v118
	v_exp_f32_e32 v119, v119
	s_nop 0
	v_pk_add_f32 v[118:119], v[118:119], 1.0 op_sel_hi:[1,0]
	s_nop 0
	v_rcp_f32_e32 v121, v119
	s_nop 0
	v_mul_f32_e32 v119, 1.0, v121
	v_rcp_f32_e32 v121, v118
	s_nop 0
	v_mul_f32_e32 v118, 1.0, v121
	v_cvt_pk_bf16_f32 v118, v118, v119
	v_mul_f32_e32 v119, 0xbfb8aa3b, v128
	v_exp_f32_e32 v120, v119
	v_mul_f32_e32 v119, 0xbfb8aa3b, v129
	v_exp_f32_e32 v121, v119
	s_nop 0
	v_pk_add_f32 v[120:121], v[120:121], 1.0 op_sel_hi:[1,0]
	s_nop 0
	v_rcp_f32_e32 v122, v121
	s_nop 0
	v_mul_f32_e32 v119, 1.0, v122
	v_rcp_f32_e32 v122, v120
	s_nop 0
	v_mul_f32_e32 v120, 1.0, v122
	v_cvt_pk_bf16_f32 v119, v120, v119
	v_mul_f32_e32 v120, 0xbfb8aa3b, v130
	v_mul_f32_e32 v121, 0xbfb8aa3b, v131
	v_exp_f32_e32 v120, v120
	v_exp_f32_e32 v121, v121
	s_nop 0
	v_pk_add_f32 v[120:121], v[120:121], 1.0 op_sel_hi:[1,0]
	s_nop 0
	v_rcp_f32_e32 v123, v121
	s_nop 0
	v_mul_f32_e32 v121, 1.0, v123
	v_rcp_f32_e32 v123, v120
	s_nop 0
	v_mul_f32_e32 v120, 1.0, v123
	v_cvt_pk_bf16_f32 v120, v120, v121
	v_rcp_f32_e32 v122, v101
	s_nop 0
	v_mul_f32_e32 v101, 1.0, v122
	v_rcp_f32_e32 v122, v100
	s_nop 0
	v_mul_f32_e32 v100, 1.0, v122
	v_cvt_pk_bf16_f32 v100, v100, v101
	v_mul_f32_e32 v101, 0xbfb8aa3b, v102
	v_exp_f32_e32 v102, v101
	v_mul_f32_e32 v101, 0xbfb8aa3b, v103
	v_exp_f32_e32 v103, v101
	s_nop 0
	v_pk_add_f32 v[102:103], v[102:103], 1.0 op_sel_hi:[1,0]
	s_nop 0
	v_rcp_f32_e32 v121, v103
	s_nop 0
	v_mul_f32_e32 v101, 1.0, v121
	v_rcp_f32_e32 v121, v102
	s_nop 0
	v_mul_f32_e32 v102, 1.0, v121
	v_cvt_pk_bf16_f32 v101, v102, v101
	v_mul_f32_e32 v102, 0xbfb8aa3b, v104
	v_mul_f32_e32 v103, 0xbfb8aa3b, v105
	v_exp_f32_e32 v102, v102
	v_exp_f32_e32 v103, v103
	s_nop 0
	v_pk_add_f32 v[102:103], v[102:103], 1.0 op_sel_hi:[1,0]
	s_nop 0
	v_rcp_f32_e32 v105, v103
	s_nop 0
	v_mul_f32_e32 v103, 1.0, v105
	v_rcp_f32_e32 v105, v102
	s_nop 0
	v_mul_f32_e32 v102, 1.0, v105
	v_cvt_pk_bf16_f32 v102, v102, v103
; DEV float bflo(uint32_t u) { return __uint_as_float(u << 16); }
; DEV float bfhi(uint32_t u) { return __uint_as_float(u & 0xffff0000u); }
; __device__ void phase_merge(PRef p, int l, const bf16* H2, bf16* M, bf16* sA, bf16* sB) {
;     ...
; #pragma unroll
;         for (int a = 0; a < 2; a++)
; #pragma unroll
;           for (int bb = 0; bb < 2; bb++)
; #pragma unroll
;             for (int r = 0; r < 8; r++) {
;               float g0 = __fdividef(1.f, 1.f + __expf(-a2[a][bb][2 * r]));
;               float g1 = __fdividef(1.f, 1.f + __expf(-a2[a][bb][2 * r + 1]));
;               gp[a][bb][r] = pack2(g0, g1);
;             }
;       }
;       f32x16 a1[2][2];
;       zero_acc<2>(a1);
;       gemm_tile<2, false>(a1, U + (size_t)rt * 128 * ldu, ldu, p.WBO + ((size_t)n * 1024 + ct * 128) * 512, 512, 512, sA, sB);
; #pragma unroll
;       for (int a = 0; a < 2; a++)
; #pragma unroll
;         for (int bb = 0; bb < 2; bb++)
; #pragma unroll
;           for (int r = 0; r < 8; r++) {
;             a1[a][bb][2 * r] *= bflo(gp[a][bb][r]);
;             a1[a][bb][2 * r + 1] *= bfhi(gp[a][bb][r]);
;           }
	v_mul_f32_e32 v103, 0xbfb8aa3b, v106
	v_exp_f32_e32 v104, v103
	v_mul_f32_e32 v103, 0xbfb8aa3b, v107
	v_exp_f32_e32 v105, v103
	s_nop 0
	v_pk_add_f32 v[104:105], v[104:105], 1.0 op_sel_hi:[1,0]
	s_nop 0
	v_rcp_f32_e32 v106, v105
	s_nop 0
	v_mul_f32_e32 v103, 1.0, v106
	v_rcp_f32_e32 v106, v104
	s_nop 0
	v_mul_f32_e32 v104, 1.0, v106
	v_cvt_pk_bf16_f32 v103, v104, v103
	v_mul_f32_e32 v104, 0xbfb8aa3b, v108
	v_mul_f32_e32 v105, 0xbfb8aa3b, v109
	v_exp_f32_e32 v104, v104
	v_exp_f32_e32 v105, v105
	s_nop 0
	v_pk_add_f32 v[104:105], v[104:105], 1.0 op_sel_hi:[1,0]
	s_nop 0
	v_rcp_f32_e32 v107, v105
	s_nop 0
	v_mul_f32_e32 v105, 1.0, v107
	v_rcp_f32_e32 v107, v104
	s_nop 0
	v_mul_f32_e32 v104, 1.0, v107
	v_cvt_pk_bf16_f32 v104, v104, v105
	v_mul_f32_e32 v105, 0xbfb8aa3b, v110
	v_exp_f32_e32 v106, v105
	v_mul_f32_e32 v105, 0xbfb8aa3b, v111
	v_exp_f32_e32 v107, v105
	s_nop 0
	v_pk_add_f32 v[106:107], v[106:107], 1.0 op_sel_hi:[1,0]
	s_nop 0
	v_rcp_f32_e32 v108, v107
	s_nop 0
	v_mul_f32_e32 v105, 1.0, v108
	v_rcp_f32_e32 v108, v106
	s_nop 0
	v_mul_f32_e32 v106, 1.0, v108
	v_cvt_pk_bf16_f32 v105, v106, v105
	v_mul_f32_e32 v106, 0xbfb8aa3b, v112
	v_mul_f32_e32 v107, 0xbfb8aa3b, v113
	v_exp_f32_e32 v106, v106
	v_exp_f32_e32 v107, v107
	s_nop 0
	v_pk_add_f32 v[106:107], v[106:107], 1.0 op_sel_hi:[1,0]
	s_nop 0
	v_rcp_f32_e32 v109, v107
	s_nop 0
	v_mul_f32_e32 v107, 1.0, v109
	v_rcp_f32_e32 v109, v106
	s_nop 0
	v_mul_f32_e32 v106, 1.0, v109
	v_cvt_pk_bf16_f32 v106, v106, v107
	v_mul_f32_e32 v107, 0xbfb8aa3b, v114
	v_exp_f32_e32 v108, v107
	v_mul_f32_e32 v107, 0xbfb8aa3b, v115
	v_exp_f32_e32 v109, v107
	s_nop 0
	v_pk_add_f32 v[108:109], v[108:109], 1.0 op_sel_hi:[1,0]
	s_nop 0
	v_rcp_f32_e32 v110, v109
	s_nop 0
	v_mul_f32_e32 v107, 1.0, v110
	v_rcp_f32_e32 v110, v108
	s_nop 0
	v_mul_f32_e32 v108, 1.0, v110
	v_cvt_pk_bf16_f32 v107, v108, v107
	v_rcp_f32_e32 v109, v69
	s_nop 0
	v_mul_f32_e32 v69, 1.0, v109
	v_rcp_f32_e32 v109, v68
	s_nop 0
	v_mul_f32_e32 v68, 1.0, v109
	v_cvt_pk_bf16_f32 v68, v68, v69
	v_mul_f32_e32 v69, 0xbfb8aa3b, v70
	v_exp_f32_e32 v70, v69
	v_mul_f32_e32 v69, 0xbfb8aa3b, v71
	v_exp_f32_e32 v71, v69
	s_nop 0
	v_pk_add_f32 v[70:71], v[70:71], 1.0 op_sel_hi:[1,0]
	s_nop 0
	v_rcp_f32_e32 v108, v71
	s_nop 0
	v_mul_f32_e32 v69, 1.0, v108
	v_rcp_f32_e32 v108, v70
	s_nop 0
	v_mul_f32_e32 v70, 1.0, v108
	v_cvt_pk_bf16_f32 v69, v70, v69
	v_mul_f32_e32 v70, 0xbfb8aa3b, v72
	v_mul_f32_e32 v71, 0xbfb8aa3b, v73
	v_exp_f32_e32 v70, v70
	v_exp_f32_e32 v71, v71
	s_nop 0
	v_pk_add_f32 v[70:71], v[70:71], 1.0 op_sel_hi:[1,0]
	s_nop 0
	v_rcp_f32_e32 v73, v71
	s_nop 0
	v_mul_f32_e32 v71, 1.0, v73
	v_rcp_f32_e32 v73, v70
	s_nop 0
	v_mul_f32_e32 v70, 1.0, v73
	v_cvt_pk_bf16_f32 v70, v70, v71
	v_mul_f32_e32 v71, 0xbfb8aa3b, v74
	v_exp_f32_e32 v72, v71
	v_mul_f32_e32 v71, 0xbfb8aa3b, v75
	v_exp_f32_e32 v73, v71
	s_nop 0
	v_pk_add_f32 v[72:73], v[72:73], 1.0 op_sel_hi:[1,0]
	s_nop 0
	v_rcp_f32_e32 v74, v73
	s_nop 0
	v_mul_f32_e32 v71, 1.0, v74
	v_rcp_f32_e32 v74, v72
	s_nop 0
	v_mul_f32_e32 v72, 1.0, v74
	v_cvt_pk_bf16_f32 v71, v72, v71
	v_mul_f32_e32 v72, 0xbfb8aa3b, v76
	v_mul_f32_e32 v73, 0xbfb8aa3b, v77
	v_exp_f32_e32 v72, v72
	v_exp_f32_e32 v73, v73
	s_nop 0
	v_pk_add_f32 v[72:73], v[72:73], 1.0 op_sel_hi:[1,0]
	s_nop 0
	v_rcp_f32_e32 v75, v73
	s_nop 0
	v_mul_f32_e32 v73, 1.0, v75
	v_rcp_f32_e32 v75, v72
	s_nop 0
	v_mul_f32_e32 v72, 1.0, v75
	v_cvt_pk_bf16_f32 v72, v72, v73
	v_mul_f32_e32 v73, 0xbfb8aa3b, v78
	v_exp_f32_e32 v74, v73
	v_mul_f32_e32 v73, 0xbfb8aa3b, v79
	v_exp_f32_e32 v75, v73
	s_nop 0
	v_pk_add_f32 v[74:75], v[74:75], 1.0 op_sel_hi:[1,0]
	s_nop 0
	v_rcp_f32_e32 v76, v75
	s_nop 0
	v_mul_f32_e32 v73, 1.0, v76
	v_rcp_f32_e32 v76, v74
	s_nop 0
	v_mul_f32_e32 v74, 1.0, v76
	v_cvt_pk_bf16_f32 v73, v74, v73
	v_mul_f32_e32 v74, 0xbfb8aa3b, v80
	v_mul_f32_e32 v75, 0xbfb8aa3b, v81
	v_exp_f32_e32 v74, v74
	v_exp_f32_e32 v75, v75
	s_nop 0
	v_pk_add_f32 v[74:75], v[74:75], 1.0 op_sel_hi:[1,0]
	s_nop 0
	v_rcp_f32_e32 v77, v75
	s_nop 0
	v_mul_f32_e32 v75, 1.0, v77
	v_rcp_f32_e32 v77, v74
	s_nop 0
	v_mul_f32_e32 v74, 1.0, v77
	v_cvt_pk_bf16_f32 v74, v74, v75
	v_mul_f32_e32 v75, 0xbfb8aa3b, v82
	v_exp_f32_e32 v76, v75
	v_mul_f32_e32 v75, 0xbfb8aa3b, v83
	v_exp_f32_e32 v77, v75
	s_nop 0
	v_pk_add_f32 v[76:77], v[76:77], 1.0 op_sel_hi:[1,0]
	s_nop 0
	v_rcp_f32_e32 v78, v77
	s_nop 0
	v_mul_f32_e32 v75, 1.0, v78
	v_rcp_f32_e32 v78, v76
	s_nop 0
	v_mul_f32_e32 v76, 1.0, v78
	v_cvt_pk_bf16_f32 v75, v76, v75
	v_rcp_f32_e32 v77, v5
	s_nop 0
	v_mul_f32_e32 v5, 1.0, v77
	v_rcp_f32_e32 v77, v4
	s_nop 0
	v_mul_f32_e32 v4, 1.0, v77
	v_cvt_pk_bf16_f32 v4, v4, v5
	v_mul_f32_e32 v5, 0xbfb8aa3b, v6
	v_exp_f32_e32 v6, v5
	v_mul_f32_e32 v5, 0xbfb8aa3b, v7
	v_exp_f32_e32 v7, v5
	s_nop 0
	v_pk_add_f32 v[6:7], v[6:7], 1.0 op_sel_hi:[1,0]
	s_nop 0
	v_rcp_f32_e32 v76, v7
	s_nop 0
	v_mul_f32_e32 v5, 1.0, v76
	v_rcp_f32_e32 v76, v6
	s_nop 0
	v_mul_f32_e32 v6, 1.0, v76
	v_cvt_pk_bf16_f32 v5, v6, v5
	v_mul_f32_e32 v6, 0xbfb8aa3b, v8
	v_mul_f32_e32 v7, 0xbfb8aa3b, v9
	v_exp_f32_e32 v6, v6
	v_exp_f32_e32 v7, v7
	v_and_b32_e32 v79, 0xffff0000, v100
	v_pk_add_f32 v[6:7], v[6:7], 1.0 op_sel_hi:[1,0]
	s_nop 0
	v_rcp_f32_e32 v9, v7
	s_nop 0
	v_mul_f32_e32 v7, 1.0, v9
	v_rcp_f32_e32 v9, v6
	s_nop 0
	v_mul_f32_e32 v6, 1.0, v9
	v_cvt_pk_bf16_f32 v6, v6, v7
	v_mul_f32_e32 v7, 0xbfb8aa3b, v10
	v_exp_f32_e32 v8, v7
	v_mul_f32_e32 v7, 0xbfb8aa3b, v11
	v_exp_f32_e32 v9, v7
	v_lshlrev_b32_e32 v78, 16, v100
	v_pk_mul_f32 v[52:53], v[52:53], v[78:79]
	v_lshlrev_b32_e32 v78, 16, v101
	v_pk_add_f32 v[8:9], v[8:9], 1.0 op_sel_hi:[1,0]
	v_and_b32_e32 v79, 0xffff0000, v101
	v_div_scale_f32 v7, s[0:1], v9, v9, 1.0
; DEV float bflo(uint32_t u) { return __uint_as_float(u << 16); }
; DEV float bfhi(uint32_t u) { return __uint_as_float(u & 0xffff0000u); }
; __device__ void phase_merge(PRef p, int l, const bf16* H2, bf16* M, bf16* sA, bf16* sB) {
;     ...
; #pragma unroll
;         for (int a = 0; a < 2; a++)
; #pragma unroll
;           for (int bb = 0; bb < 2; bb++)
; #pragma unroll
;             for (int r = 0; r < 8; r++) {
;               float g0 = __fdividef(1.f, 1.f + __expf(-a2[a][bb][2 * r]));
;               float g1 = __fdividef(1.f, 1.f + __expf(-a2[a][bb][2 * r + 1]));
;               gp[a][bb][r] = pack2(g0, g1);
;             }
;       }
;       f32x16 a1[2][2];
;       zero_acc<2>(a1);
;       gemm_tile<2, false>(a1, U + (size_t)rt * 128 * ldu, ldu, p.WBO + ((size_t)n * 1024 + ct * 128) * 512, 512, 512, sA, sB);
; #pragma unroll
;       for (int a = 0; a < 2; a++)
; #pragma unroll
;         for (int bb = 0; bb < 2; bb++)
; #pragma unroll
;           for (int r = 0; r < 8; r++) {
;             a1[a][bb][2 * r] *= bflo(gp[a][bb][r]);
;             a1[a][bb][2 * r + 1] *= bfhi(gp[a][bb][r]);
;           }
	v_rcp_f32_e32 v10, v7
	v_pk_mul_f32 v[54:55], v[54:55], v[78:79]
	v_lshlrev_b32_e32 v78, 16, v102
	v_and_b32_e32 v79, 0xffff0000, v102
	v_fma_f32 v11, -v7, v10, 1.0
	v_fmac_f32_e32 v10, v11, v10
	v_div_scale_f32 v11, vcc, 1.0, v9, 1.0
	v_mul_f32_e32 v76, v11, v10
	v_fma_f32 v77, -v7, v76, v11
	v_fmac_f32_e32 v76, v77, v10
	v_fma_f32 v7, -v7, v76, v11
	v_div_fmas_f32 v7, v7, v10, v76
	v_div_fixup_f32 v7, v7, v9, 1.0
	v_div_scale_f32 v9, s[0:1], v8, v8, 1.0
	v_rcp_f32_e32 v10, v9
	v_pk_mul_f32 v[56:57], v[56:57], v[78:79]
	v_lshlrev_b32_e32 v78, 16, v103
	v_and_b32_e32 v79, 0xffff0000, v103
	v_fma_f32 v11, -v9, v10, 1.0
	v_fmac_f32_e32 v10, v11, v10
	v_div_scale_f32 v11, vcc, 1.0, v8, 1.0
	v_mul_f32_e32 v76, v11, v10
	v_fma_f32 v77, -v9, v76, v11
	v_fmac_f32_e32 v76, v77, v10
	v_fma_f32 v9, -v9, v76, v11
	v_div_fmas_f32 v9, v9, v10, v76
	v_div_fixup_f32 v8, v9, v8, 1.0
	v_cvt_pk_bf16_f32 v7, v8, v7
	v_mul_f32_e32 v8, 0xbfb8aa3b, v12
	v_mul_f32_e32 v9, 0xbfb8aa3b, v13
	v_exp_f32_e32 v8, v8
	v_exp_f32_e32 v9, v9
	v_pk_mul_f32 v[58:59], v[58:59], v[78:79]
	v_lshlrev_b32_e32 v78, 16, v104
	v_and_b32_e32 v79, 0xffff0000, v104
	v_pk_add_f32 v[8:9], v[8:9], 1.0 op_sel_hi:[1,0]
	v_pk_mul_f32 v[60:61], v[60:61], v[78:79]
	v_div_scale_f32 v10, s[0:1], v9, v9, 1.0
	v_rcp_f32_e32 v11, v10
	v_lshlrev_b32_e32 v78, 16, v105
	v_and_b32_e32 v79, 0xffff0000, v105
	v_pk_mul_f32 v[62:63], v[62:63], v[78:79]
	v_fma_f32 v12, -v10, v11, 1.0
	v_fmac_f32_e32 v11, v12, v11
	v_div_scale_f32 v12, vcc, 1.0, v9, 1.0
	v_mul_f32_e32 v13, v12, v11
	v_fma_f32 v76, -v10, v13, v12
	v_fmac_f32_e32 v13, v76, v11
	v_fma_f32 v10, -v10, v13, v12
	v_div_fmas_f32 v10, v10, v11, v13
	v_div_fixup_f32 v9, v10, v9, 1.0
	v_div_scale_f32 v10, s[0:1], v8, v8, 1.0
	v_rcp_f32_e32 v11, v10
	v_lshlrev_b32_e32 v78, 16, v106
	v_and_b32_e32 v79, 0xffff0000, v106
	v_pk_mul_f32 v[64:65], v[64:65], v[78:79]
	v_fma_f32 v12, -v10, v11, 1.0
	v_fmac_f32_e32 v11, v12, v11
	v_div_scale_f32 v12, vcc, 1.0, v8, 1.0
	v_mul_f32_e32 v13, v12, v11
	v_fma_f32 v76, -v10, v13, v12
	v_fmac_f32_e32 v13, v76, v11
	v_fma_f32 v10, -v10, v13, v12
	v_div_fmas_f32 v10, v10, v11, v13
	v_div_fixup_f32 v8, v10, v8, 1.0
	v_cvt_pk_bf16_f32 v80, v8, v9
	v_mul_f32_e32 v8, 0xbfb8aa3b, v14
	v_mul_f32_e32 v9, 0xbfb8aa3b, v15
	v_exp_f32_e32 v8, v8
	v_exp_f32_e32 v9, v9
	v_lshlrev_b32_e32 v78, 16, v107
	v_and_b32_e32 v79, 0xffff0000, v107
	v_pk_mul_f32 v[66:67], v[66:67], v[78:79]
	v_pk_add_f32 v[8:9], v[8:9], 1.0 op_sel_hi:[1,0]
	v_lshlrev_b32_e32 v78, 16, v68
	v_div_scale_f32 v10, s[0:1], v9, v9, 1.0
	v_rcp_f32_e32 v11, v10
	v_and_b32_e32 v79, 0xffff0000, v68
	v_lshlrev_b32_e32 v68, 16, v69
	v_and_b32_e32 v69, 0xffff0000, v69
	v_fma_f32 v12, -v10, v11, 1.0
	v_fmac_f32_e32 v11, v12, v11
	v_div_scale_f32 v12, vcc, 1.0, v9, 1.0
	v_mul_f32_e32 v13, v12, v11
	v_fma_f32 v14, -v10, v13, v12
	v_fmac_f32_e32 v13, v14, v11
	v_fma_f32 v10, -v10, v13, v12
	v_div_fmas_f32 v10, v10, v11, v13
	v_div_fixup_f32 v9, v10, v9, 1.0
	v_div_scale_f32 v10, s[0:1], v8, v8, 1.0
	v_rcp_f32_e32 v11, v10
	v_pk_mul_f32 v[38:39], v[38:39], v[68:69]
	v_lshlrev_b32_e32 v68, 16, v70
	v_and_b32_e32 v69, 0xffff0000, v70
	v_fma_f32 v12, -v10, v11, 1.0
	v_fmac_f32_e32 v11, v12, v11
	v_div_scale_f32 v12, vcc, 1.0, v8, 1.0
	v_mul_f32_e32 v13, v12, v11
	v_fma_f32 v14, -v10, v13, v12
	v_fmac_f32_e32 v13, v14, v11
	v_fma_f32 v10, -v10, v13, v12
	v_div_fmas_f32 v10, v10, v11, v13
	v_div_fixup_f32 v8, v10, v8, 1.0
	v_cvt_pk_bf16_f32 v81, v8, v9
	v_mul_f32_e32 v8, 0xbfb8aa3b, v16
	v_mul_f32_e32 v9, 0xbfb8aa3b, v17
	v_exp_f32_e32 v8, v8
	v_exp_f32_e32 v9, v9
	v_pk_mul_f32 v[40:41], v[40:41], v[68:69]
	v_lshlrev_b32_e32 v68, 16, v71
	v_and_b32_e32 v69, 0xffff0000, v71
	v_pk_add_f32 v[8:9], v[8:9], 1.0 op_sel_hi:[1,0]
	v_pk_mul_f32 v[42:43], v[42:43], v[68:69]
	v_div_scale_f32 v10, s[0:1], v9, v9, 1.0
	v_rcp_f32_e32 v11, v10
	v_lshlrev_b32_e32 v68, 16, v72
	v_and_b32_e32 v69, 0xffff0000, v72
	v_pk_mul_f32 v[44:45], v[44:45], v[68:69]
	v_fma_f32 v12, -v10, v11, 1.0
	v_fmac_f32_e32 v11, v12, v11
	v_div_scale_f32 v12, vcc, 1.0, v9, 1.0
	v_mul_f32_e32 v13, v12, v11
	v_fma_f32 v14, -v10, v13, v12
	v_fmac_f32_e32 v13, v14, v11
	v_fma_f32 v10, -v10, v13, v12
	v_div_fmas_f32 v10, v10, v11, v13
	v_div_fixup_f32 v9, v10, v9, 1.0
	v_div_scale_f32 v10, s[0:1], v8, v8, 1.0
	v_rcp_f32_e32 v11, v10
	v_lshlrev_b32_e32 v68, 16, v73
	v_and_b32_e32 v69, 0xffff0000, v73
	v_pk_mul_f32 v[46:47], v[46:47], v[68:69]
	v_fma_f32 v12, -v10, v11, 1.0
	v_fmac_f32_e32 v11, v12, v11
	v_div_scale_f32 v12, vcc, 1.0, v8, 1.0
	v_mul_f32_e32 v13, v12, v11
	v_fma_f32 v14, -v10, v13, v12
	v_fmac_f32_e32 v13, v14, v11
	v_fma_f32 v10, -v10, v13, v12
	v_div_fmas_f32 v10, v10, v11, v13
	v_div_fixup_f32 v8, v10, v8, 1.0
	v_cvt_pk_bf16_f32 v82, v8, v9
	v_mul_f32_e32 v8, 0xbfb8aa3b, v18
	v_mul_f32_e32 v9, 0xbfb8aa3b, v19
	v_exp_f32_e32 v8, v8
	v_exp_f32_e32 v9, v9
	v_lshlrev_b32_e32 v68, 16, v74
	v_and_b32_e32 v69, 0xffff0000, v74
	v_pk_mul_f32 v[48:49], v[48:49], v[68:69]
	v_pk_add_f32 v[8:9], v[8:9], 1.0 op_sel_hi:[1,0]
	v_lshlrev_b32_e32 v68, 16, v75
	v_div_scale_f32 v10, s[0:1], v9, v9, 1.0
	v_rcp_f32_e32 v11, v10
	v_and_b32_e32 v69, 0xffff0000, v75
	v_pk_mul_f32 v[50:51], v[50:51], v[68:69]
	v_lshlrev_b32_e32 v68, 16, v4
	v_fma_f32 v12, -v10, v11, 1.0
	v_fmac_f32_e32 v11, v12, v11
	v_div_scale_f32 v12, vcc, 1.0, v9, 1.0
	v_mul_f32_e32 v13, v12, v11
	v_fma_f32 v14, -v10, v13, v12
	v_fmac_f32_e32 v13, v14, v11
	v_fma_f32 v10, -v10, v13, v12
	v_div_fmas_f32 v10, v10, v11, v13
	v_div_fixup_f32 v9, v10, v9, 1.0
	v_div_scale_f32 v10, s[0:1], v8, v8, 1.0
	v_rcp_f32_e32 v11, v10
	v_and_b32_e32 v69, 0xffff0000, v4
; DEV int tid_() { int t = threadIdx.x; asm volatile("" : "+v"(t)); return t; }
; DEV float bflo(uint32_t u) { return __uint_as_float(u << 16); }
; DEV float bfhi(uint32_t u) { return __uint_as_float(u & 0xffff0000u); }
; template <int NI>
; DEV void stage_tile(const f32x16 (&acc)[2][NI], bf16* sC) {
;   constexpr int LDC = NI * 64 + 8;
;   int tid = tid_();
;   int lane = tid & 63, wave = tid >> 6;
;   int wm = wave >> 1, wn = wave & 1;
;   __syncthreads();
; #pragma unroll
;   for (int mi = 0; mi < 2; mi++)
; #pragma unroll
;     for (int ni = 0; ni < NI; ni++)
; #pragma unroll
;       for (int g = 0; g < 4; g++) {
;         int row = wm * 64 + mi * 32 + (lane & 31);
;         int col = wn * NI * 32 + ni * 32 + 8 * g + 4 * (lane >> 5);
;         uint2 v;
;         v.x = pack2(acc[mi][ni][4 * g], acc[mi][ni][4 * g + 1]);
;         v.y = pack2(acc[mi][ni][4 * g + 2], acc[mi][ni][4 * g + 3]);
;         *(uint2*)(sC + row * LDC + col) = v;
;       }
;   __syncthreads();
; __device__ void phase_merge(PRef p, int l, const bf16* H2, bf16* M, bf16* sA, bf16* sB) {
;     ...
;       stage_tile<2>(a1, sA);
;       TILE_CHUNKS(2, sA, {
;         u32x4* mp = (u32x4*)(M + (size_t)(rt * 128 + trow) * 1024 + ct * 128 + tcol);
;         u32x4 ov = cv;
;         if (n != 0) {
;           u32x4 pv = *mp;
;           _Pragma("unroll") for (int j = 0; j < 4; j++) ov[j] = pack2(bflo(pv[j]) + bflo(cv[j]), bfhi(pv[j]) + bfhi(cv[j]));
;         }
;         *mp = ov;
;       })
	v_lshlrev_b32_e32 v4, 16, v5
	v_and_b32_e32 v5, 0xffff0000, v5
	v_fma_f32 v12, -v10, v11, 1.0
	v_fmac_f32_e32 v11, v12, v11
	v_div_scale_f32 v12, vcc, 1.0, v8, 1.0
	v_mul_f32_e32 v13, v12, v11
	v_fma_f32 v14, -v10, v13, v12
	v_fmac_f32_e32 v13, v14, v11
	v_fma_f32 v10, -v10, v13, v12
	v_pk_mul_f32 v[4:5], v[22:23], v[4:5]
	v_lshlrev_b32_e32 v22, 16, v6
	v_and_b32_e32 v23, 0xffff0000, v6
	v_div_fmas_f32 v10, v10, v11, v13
	v_pk_mul_f32 v[22:23], v[24:25], v[22:23]
	v_lshlrev_b32_e32 v24, 16, v80
	v_and_b32_e32 v25, 0xffff0000, v80
	v_div_fixup_f32 v8, v10, v8, 1.0
	v_lshlrev_b32_e32 v10, 16, v2
	v_and_b32_e32 v11, 0xffff0000, v2
	v_pk_mul_f32 v[24:25], v[28:29], v[24:25]
	v_lshlrev_b32_e32 v28, 16, v82
	v_and_b32_e32 v29, 0xffff0000, v82
	v_mov_b32_e32 v2, v196
	v_pk_mul_f32 v[28:29], v[32:33], v[28:29]
	v_cvt_pk_bf16_f32 v83, v8, v9
	v_lshrrev_b32_e32 v32, 1, v2
	v_and_b32_e32 v33, 31, v2
	v_and_or_b32 v32, v32, s75, v33
	v_and_b32_e32 v33, 64, v2
	v_lshrrev_b32_e32 v2, 2, v2
	v_lshlrev_b32_e32 v8, 16, v0
	v_and_b32_e32 v9, 0xffff0000, v0
	v_lshlrev_b32_e32 v0, 16, v1
	v_and_b32_e32 v1, 0xffff0000, v1
	v_lshlrev_b32_e32 v12, 16, v116
	v_and_b32_e32 v13, 0xffff0000, v116
	v_and_b32_e32 v2, 8, v2
	v_pk_mul_f32 v[8:9], v[84:85], v[8:9]
	v_pk_mul_f32 v[0:1], v[86:87], v[0:1]
	v_pk_mul_f32 v[10:11], v[88:89], v[10:11]
	v_pk_mul_f32 v[12:13], v[90:91], v[12:13]
	v_lshlrev_b32_e32 v14, 16, v117
	v_and_b32_e32 v15, 0xffff0000, v117
	v_lshlrev_b32_e32 v16, 16, v118
	v_and_b32_e32 v17, 0xffff0000, v118
	v_lshlrev_b32_e32 v18, 16, v119
	v_and_b32_e32 v19, 0xffff0000, v119
	v_lshlrev_b32_e32 v76, 16, v120
	v_and_b32_e32 v77, 0xffff0000, v120
	v_lshl_or_b32 v2, v33, 1, v2
	v_pk_mul_f32 v[14:15], v[92:93], v[14:15]
	v_pk_mul_f32 v[16:17], v[94:95], v[16:17]
	v_pk_mul_f32 v[18:19], v[96:97], v[18:19]
	v_pk_mul_f32 v[76:77], v[98:99], v[76:77]
	v_mad_u64_u32 v[32:33], s[0:1], v32, s52, v[2:3]
	v_cvt_pk_bf16_f32 v8, v8, v9
	v_cvt_pk_bf16_f32 v9, v0, v1
	v_cvt_pk_bf16_f32 v0, v10, v11
	v_cvt_pk_bf16_f32 v1, v12, v13
	s_barrier
	ds_write2_b64 v32, v[8:9], v[0:1] offset1:2
	v_cvt_pk_bf16_f32 v0, v14, v15
	v_cvt_pk_bf16_f32 v1, v16, v17
	v_cvt_pk_bf16_f32 v8, v18, v19
	v_cvt_pk_bf16_f32 v9, v76, v77
	ds_write2_b64 v32, v[0:1], v[8:9] offset0:4 offset1:6
	v_cvt_pk_bf16_f32 v0, v52, v53
	v_cvt_pk_bf16_f32 v1, v54, v55
	v_cvt_pk_bf16_f32 v8, v56, v57
	v_cvt_pk_bf16_f32 v9, v58, v59
	v_pk_mul_f32 v[36:37], v[36:37], v[78:79]
	v_lshlrev_b32_e32 v6, 16, v7
	v_and_b32_e32 v7, 0xffff0000, v7
	ds_write2_b64 v32, v[0:1], v[8:9] offset0:8 offset1:10
	v_cvt_pk_bf16_f32 v0, v60, v61
	v_cvt_pk_bf16_f32 v1, v62, v63
	v_cvt_pk_bf16_f32 v8, v64, v65
	v_cvt_pk_bf16_f32 v9, v66, v67
	v_pk_mul_f32 v[6:7], v[26:27], v[6:7]
	v_lshlrev_b32_e32 v26, 16, v81
	v_and_b32_e32 v27, 0xffff0000, v81
	ds_write2_b64 v32, v[0:1], v[8:9] offset0:12 offset1:14
	v_cvt_pk_bf16_f32 v0, v36, v37
	v_cvt_pk_bf16_f32 v1, v38, v39
	v_cvt_pk_bf16_f32 v8, v40, v41
	v_cvt_pk_bf16_f32 v9, v42, v43
	v_add_u32_e32 v2, 0x2000, v32
	v_pk_mul_f32 v[20:21], v[20:21], v[68:69]
	v_pk_mul_f32 v[26:27], v[30:31], v[26:27]
	v_lshlrev_b32_e32 v30, 16, v83
	v_and_b32_e32 v31, 0xffff0000, v83
	ds_write2_b64 v2, v[0:1], v[8:9] offset0:64 offset1:66
	v_cvt_pk_bf16_f32 v0, v44, v45
	v_cvt_pk_bf16_f32 v1, v46, v47
	v_cvt_pk_bf16_f32 v8, v48, v49
	v_cvt_pk_bf16_f32 v9, v50, v51
	v_pk_mul_f32 v[30:31], v[34:35], v[30:31]
	ds_write2_b64 v2, v[0:1], v[8:9] offset0:68 offset1:70
	v_cvt_pk_bf16_f32 v0, v20, v21
	v_cvt_pk_bf16_f32 v1, v4, v5
	v_cvt_pk_bf16_f32 v4, v22, v23
	v_cvt_pk_bf16_f32 v5, v6, v7
	ds_write2_b64 v2, v[0:1], v[4:5] offset0:72 offset1:74
	v_cvt_pk_bf16_f32 v0, v24, v25
	v_cvt_pk_bf16_f32 v1, v26, v27
	v_cvt_pk_bf16_f32 v4, v28, v29
	v_cvt_pk_bf16_f32 v5, v30, v31
	ds_write2_b64 v2, v[0:1], v[4:5] offset0:76 offset1:78
	v_mov_b32_e32 v2, v196
	s_waitcnt lgkmcnt(0)
	s_barrier
	v_lshrrev_b32_e32 v60, 4, v196
	v_and_b32_e32 v61, 15, v196
	v_mul_lo_u32 v62, v60, s52
	v_lshl_add_u32 v62, v61, 4, v62
	v_lshlrev_b32_e32 v63, 11, v60
	v_lshl_add_u32 v63, v61, 4, v63
	s_lshl_b32 s0, s94, 11
	s_add_u32 s98, s22, s0
	s_addc_u32 s99, s23, 0
	s_mov_b64 s[100:101], s[98:99]
	s_and_b64 vcc, exec, s[54:55]
	s_cbranch_vccz .Lmerge_first
	global_load_dwordx4 v[20:23], v63, s[98:99]
	s_add_u32 s98, s98, 0x8000
	s_addc_u32 s99, s99, 0
	global_load_dwordx4 v[24:27], v63, s[98:99]
	s_add_u32 s98, s98, 0x8000
	s_addc_u32 s99, s99, 0
	global_load_dwordx4 v[28:31], v63, s[98:99]
	s_add_u32 s98, s98, 0x8000
	s_addc_u32 s99, s99, 0
	global_load_dwordx4 v[32:35], v63, s[98:99]
	s_add_u32 s98, s98, 0x8000
	s_addc_u32 s99, s99, 0
	global_load_dwordx4 v[36:39], v63, s[98:99]
	s_add_u32 s98, s98, 0x8000
	s_addc_u32 s99, s99, 0
	global_load_dwordx4 v[40:43], v63, s[98:99]
	s_add_u32 s98, s98, 0x8000
	s_addc_u32 s99, s99, 0
	global_load_dwordx4 v[44:47], v63, s[98:99]
	s_add_u32 s98, s98, 0x8000
	s_addc_u32 s99, s99, 0
	global_load_dwordx4 v[48:51], v63, s[98:99]
	ds_read_b128 v[4:7], v62 offset:0
	s_waitcnt vmcnt(7) lgkmcnt(0)
	v_lshlrev_b32_e32 v8, 16, v4
	v_and_b32_e32 v9, 0xffff0000, v4
	v_lshlrev_b32_e32 v10, 16, v5
	v_and_b32_e32 v11, 0xffff0000, v5
	v_lshlrev_b32_e32 v12, 16, v6
	v_and_b32_e32 v13, 0xffff0000, v6
	v_lshlrev_b32_e32 v14, 16, v7
	v_and_b32_e32 v15, 0xffff0000, v7
	v_lshlrev_b32_e32 v52, 16, v20
	v_and_b32_e32 v53, 0xffff0000, v20
	v_lshlrev_b32_e32 v54, 16, v21
	v_and_b32_e32 v55, 0xffff0000, v21
	v_lshlrev_b32_e32 v56, 16, v22
	v_and_b32_e32 v57, 0xffff0000, v22
	v_lshlrev_b32_e32 v58, 16, v23
	v_and_b32_e32 v59, 0xffff0000, v23
	v_add_f32_e32 v8, v8, v52
	v_add_f32_e32 v9, v9, v53
	v_add_f32_e32 v10, v10, v54
	v_add_f32_e32 v11, v11, v55
	v_add_f32_e32 v12, v12, v56
	v_add_f32_e32 v13, v13, v57
	v_add_f32_e32 v14, v14, v58
	v_add_f32_e32 v15, v15, v59
	v_cvt_pk_bf16_f32 v20, v8, v9
	v_cvt_pk_bf16_f32 v21, v10, v11
	v_cvt_pk_bf16_f32 v22, v12, v13
	v_cvt_pk_bf16_f32 v23, v14, v15
	global_store_dwordx4 v63, v[20:23], s[100:101]
	s_add_u32 s100, s100, 0x8000
	s_addc_u32 s101, s101, 0
	ds_read_b128 v[4:7], v62 offset:4352
	s_waitcnt vmcnt(7) lgkmcnt(0)
; DEV float bflo(uint32_t u) { return __uint_as_float(u << 16); }
; DEV float bfhi(uint32_t u) { return __uint_as_float(u & 0xffff0000u); }
; __device__ void phase_merge(PRef p, int l, const bf16* H2, bf16* M, bf16* sA, bf16* sB) {
;     ...
;       TILE_CHUNKS(2, sA, {
;         u32x4* mp = (u32x4*)(M + (size_t)(rt * 128 + trow) * 1024 + ct * 128 + tcol);
;         u32x4 ov = cv;
;         if (n != 0) {
;           u32x4 pv = *mp;
;           _Pragma("unroll") for (int j = 0; j < 4; j++) ov[j] = pack2(bflo(pv[j]) + bflo(cv[j]), bfhi(pv[j]) + bfhi(cv[j]));
;         }
;         *mp = ov;
;       })
	v_lshlrev_b32_e32 v8, 16, v4
	v_and_b32_e32 v9, 0xffff0000, v4
	v_lshlrev_b32_e32 v10, 16, v5
	v_and_b32_e32 v11, 0xffff0000, v5
	v_lshlrev_b32_e32 v12, 16, v6
	v_and_b32_e32 v13, 0xffff0000, v6
	v_lshlrev_b32_e32 v14, 16, v7
	v_and_b32_e32 v15, 0xffff0000, v7
	v_lshlrev_b32_e32 v52, 16, v24
	v_and_b32_e32 v53, 0xffff0000, v24
	v_lshlrev_b32_e32 v54, 16, v25
	v_and_b32_e32 v55, 0xffff0000, v25
	v_lshlrev_b32_e32 v56, 16, v26
	v_and_b32_e32 v57, 0xffff0000, v26
	v_lshlrev_b32_e32 v58, 16, v27
	v_and_b32_e32 v59, 0xffff0000, v27
	v_add_f32_e32 v8, v8, v52
	v_add_f32_e32 v9, v9, v53
	v_add_f32_e32 v10, v10, v54
	v_add_f32_e32 v11, v11, v55
	v_add_f32_e32 v12, v12, v56
	v_add_f32_e32 v13, v13, v57
	v_add_f32_e32 v14, v14, v58
	v_add_f32_e32 v15, v15, v59
	v_cvt_pk_bf16_f32 v24, v8, v9
	v_cvt_pk_bf16_f32 v25, v10, v11
	v_cvt_pk_bf16_f32 v26, v12, v13
	v_cvt_pk_bf16_f32 v27, v14, v15
	global_store_dwordx4 v63, v[24:27], s[100:101]
	s_add_u32 s100, s100, 0x8000
	s_addc_u32 s101, s101, 0
	ds_read_b128 v[4:7], v62 offset:8704
	s_waitcnt vmcnt(7) lgkmcnt(0)
	v_lshlrev_b32_e32 v8, 16, v4
	v_and_b32_e32 v9, 0xffff0000, v4
	v_lshlrev_b32_e32 v10, 16, v5
	v_and_b32_e32 v11, 0xffff0000, v5
	v_lshlrev_b32_e32 v12, 16, v6
	v_and_b32_e32 v13, 0xffff0000, v6
	v_lshlrev_b32_e32 v14, 16, v7
	v_and_b32_e32 v15, 0xffff0000, v7
	v_lshlrev_b32_e32 v52, 16, v28
	v_and_b32_e32 v53, 0xffff0000, v28
	v_lshlrev_b32_e32 v54, 16, v29
	v_and_b32_e32 v55, 0xffff0000, v29
	v_lshlrev_b32_e32 v56, 16, v30
	v_and_b32_e32 v57, 0xffff0000, v30
	v_lshlrev_b32_e32 v58, 16, v31
	v_and_b32_e32 v59, 0xffff0000, v31
	v_add_f32_e32 v8, v8, v52
	v_add_f32_e32 v9, v9, v53
	v_add_f32_e32 v10, v10, v54
	v_add_f32_e32 v11, v11, v55
	v_add_f32_e32 v12, v12, v56
	v_add_f32_e32 v13, v13, v57
	v_add_f32_e32 v14, v14, v58
	v_add_f32_e32 v15, v15, v59
	v_cvt_pk_bf16_f32 v28, v8, v9
	v_cvt_pk_bf16_f32 v29, v10, v11
	v_cvt_pk_bf16_f32 v30, v12, v13
	v_cvt_pk_bf16_f32 v31, v14, v15
	global_store_dwordx4 v63, v[28:31], s[100:101]
	s_add_u32 s100, s100, 0x8000
	s_addc_u32 s101, s101, 0
	ds_read_b128 v[4:7], v62 offset:13056
	s_waitcnt vmcnt(7) lgkmcnt(0)
	v_lshlrev_b32_e32 v8, 16, v4
	v_and_b32_e32 v9, 0xffff0000, v4
	v_lshlrev_b32_e32 v10, 16, v5
	v_and_b32_e32 v11, 0xffff0000, v5
	v_lshlrev_b32_e32 v12, 16, v6
	v_and_b32_e32 v13, 0xffff0000, v6
	v_lshlrev_b32_e32 v14, 16, v7
	v_and_b32_e32 v15, 0xffff0000, v7
	v_lshlrev_b32_e32 v52, 16, v32
	v_and_b32_e32 v53, 0xffff0000, v32
	v_lshlrev_b32_e32 v54, 16, v33
	v_and_b32_e32 v55, 0xffff0000, v33
	v_lshlrev_b32_e32 v56, 16, v34
	v_and_b32_e32 v57, 0xffff0000, v34
	v_lshlrev_b32_e32 v58, 16, v35
	v_and_b32_e32 v59, 0xffff0000, v35
	v_add_f32_e32 v8, v8, v52
	v_add_f32_e32 v9, v9, v53
	v_add_f32_e32 v10, v10, v54
	v_add_f32_e32 v11, v11, v55
	v_add_f32_e32 v12, v12, v56
	v_add_f32_e32 v13, v13, v57
	v_add_f32_e32 v14, v14, v58
	v_add_f32_e32 v15, v15, v59
	v_cvt_pk_bf16_f32 v32, v8, v9
	v_cvt_pk_bf16_f32 v33, v10, v11
	v_cvt_pk_bf16_f32 v34, v12, v13
	v_cvt_pk_bf16_f32 v35, v14, v15
	global_store_dwordx4 v63, v[32:35], s[100:101]
	s_add_u32 s100, s100, 0x8000
	s_addc_u32 s101, s101, 0
	ds_read_b128 v[4:7], v62 offset:17408
	s_waitcnt vmcnt(7) lgkmcnt(0)
	v_lshlrev_b32_e32 v8, 16, v4
	v_and_b32_e32 v9, 0xffff0000, v4
	v_lshlrev_b32_e32 v10, 16, v5
	v_and_b32_e32 v11, 0xffff0000, v5
	v_lshlrev_b32_e32 v12, 16, v6
	v_and_b32_e32 v13, 0xffff0000, v6
	v_lshlrev_b32_e32 v14, 16, v7
	v_and_b32_e32 v15, 0xffff0000, v7
	v_lshlrev_b32_e32 v52, 16, v36
	v_and_b32_e32 v53, 0xffff0000, v36
	v_lshlrev_b32_e32 v54, 16, v37
	v_and_b32_e32 v55, 0xffff0000, v37
	v_lshlrev_b32_e32 v56, 16, v38
	v_and_b32_e32 v57, 0xffff0000, v38
	v_lshlrev_b32_e32 v58, 16, v39
	v_and_b32_e32 v59, 0xffff0000, v39
	v_add_f32_e32 v8, v8, v52
	v_add_f32_e32 v9, v9, v53
	v_add_f32_e32 v10, v10, v54
	v_add_f32_e32 v11, v11, v55
	v_add_f32_e32 v12, v12, v56
	v_add_f32_e32 v13, v13, v57
	v_add_f32_e32 v14, v14, v58
	v_add_f32_e32 v15, v15, v59
	v_cvt_pk_bf16_f32 v36, v8, v9
	v_cvt_pk_bf16_f32 v37, v10, v11
	v_cvt_pk_bf16_f32 v38, v12, v13
	v_cvt_pk_bf16_f32 v39, v14, v15
	global_store_dwordx4 v63, v[36:39], s[100:101]
	s_add_u32 s100, s100, 0x8000
	s_addc_u32 s101, s101, 0
	ds_read_b128 v[4:7], v62 offset:21760
	s_waitcnt vmcnt(7) lgkmcnt(0)
; DEV float bflo(uint32_t u) { return __uint_as_float(u << 16); }
; DEV float bfhi(uint32_t u) { return __uint_as_float(u & 0xffff0000u); }
; __device__ void phase_merge(PRef p, int l, const bf16* H2, bf16* M, bf16* sA, bf16* sB) {
;     ...
;       TILE_CHUNKS(2, sA, {
;         u32x4* mp = (u32x4*)(M + (size_t)(rt * 128 + trow) * 1024 + ct * 128 + tcol);
;         u32x4 ov = cv;
;         if (n != 0) {
;           u32x4 pv = *mp;
;           _Pragma("unroll") for (int j = 0; j < 4; j++) ov[j] = pack2(bflo(pv[j]) + bflo(cv[j]), bfhi(pv[j]) + bfhi(cv[j]));
;         }
;         *mp = ov;
;       })
	v_lshlrev_b32_e32 v8, 16, v4
	v_and_b32_e32 v9, 0xffff0000, v4
	v_lshlrev_b32_e32 v10, 16, v5
	v_and_b32_e32 v11, 0xffff0000, v5
	v_lshlrev_b32_e32 v12, 16, v6
	v_and_b32_e32 v13, 0xffff0000, v6
	v_lshlrev_b32_e32 v14, 16, v7
	v_and_b32_e32 v15, 0xffff0000, v7
	v_lshlrev_b32_e32 v52, 16, v40
	v_and_b32_e32 v53, 0xffff0000, v40
	v_lshlrev_b32_e32 v54, 16, v41
	v_and_b32_e32 v55, 0xffff0000, v41
	v_lshlrev_b32_e32 v56, 16, v42
	v_and_b32_e32 v57, 0xffff0000, v42
	v_lshlrev_b32_e32 v58, 16, v43
	v_and_b32_e32 v59, 0xffff0000, v43
	v_add_f32_e32 v8, v8, v52
	v_add_f32_e32 v9, v9, v53
	v_add_f32_e32 v10, v10, v54
	v_add_f32_e32 v11, v11, v55
	v_add_f32_e32 v12, v12, v56
	v_add_f32_e32 v13, v13, v57
	v_add_f32_e32 v14, v14, v58
	v_add_f32_e32 v15, v15, v59
	v_cvt_pk_bf16_f32 v40, v8, v9
	v_cvt_pk_bf16_f32 v41, v10, v11
	v_cvt_pk_bf16_f32 v42, v12, v13
	v_cvt_pk_bf16_f32 v43, v14, v15
	global_store_dwordx4 v63, v[40:43], s[100:101]
	s_add_u32 s100, s100, 0x8000
	s_addc_u32 s101, s101, 0
	ds_read_b128 v[4:7], v62 offset:26112
	s_waitcnt vmcnt(7) lgkmcnt(0)
	v_lshlrev_b32_e32 v8, 16, v4
	v_and_b32_e32 v9, 0xffff0000, v4
	v_lshlrev_b32_e32 v10, 16, v5
	v_and_b32_e32 v11, 0xffff0000, v5
	v_lshlrev_b32_e32 v12, 16, v6
	v_and_b32_e32 v13, 0xffff0000, v6
	v_lshlrev_b32_e32 v14, 16, v7
	v_and_b32_e32 v15, 0xffff0000, v7
	v_lshlrev_b32_e32 v52, 16, v44
	v_and_b32_e32 v53, 0xffff0000, v44
	v_lshlrev_b32_e32 v54, 16, v45
	v_and_b32_e32 v55, 0xffff0000, v45
	v_lshlrev_b32_e32 v56, 16, v46
	v_and_b32_e32 v57, 0xffff0000, v46
	v_lshlrev_b32_e32 v58, 16, v47
	v_and_b32_e32 v59, 0xffff0000, v47
	v_add_f32_e32 v8, v8, v52
	v_add_f32_e32 v9, v9, v53
	v_add_f32_e32 v10, v10, v54
	v_add_f32_e32 v11, v11, v55
	v_add_f32_e32 v12, v12, v56
	v_add_f32_e32 v13, v13, v57
	v_add_f32_e32 v14, v14, v58
	v_add_f32_e32 v15, v15, v59
	v_cvt_pk_bf16_f32 v44, v8, v9
	v_cvt_pk_bf16_f32 v45, v10, v11
	v_cvt_pk_bf16_f32 v46, v12, v13
	v_cvt_pk_bf16_f32 v47, v14, v15
	global_store_dwordx4 v63, v[44:47], s[100:101]
	s_add_u32 s100, s100, 0x8000
	s_addc_u32 s101, s101, 0
	ds_read_b128 v[4:7], v62 offset:30464
	s_waitcnt vmcnt(7) lgkmcnt(0)
	v_lshlrev_b32_e32 v8, 16, v4
	v_and_b32_e32 v9, 0xffff0000, v4
	v_lshlrev_b32_e32 v10, 16, v5
	v_and_b32_e32 v11, 0xffff0000, v5
	v_lshlrev_b32_e32 v12, 16, v6
	v_and_b32_e32 v13, 0xffff0000, v6
	v_lshlrev_b32_e32 v14, 16, v7
	v_and_b32_e32 v15, 0xffff0000, v7
	v_lshlrev_b32_e32 v52, 16, v48
	v_and_b32_e32 v53, 0xffff0000, v48
	v_lshlrev_b32_e32 v54, 16, v49
	v_and_b32_e32 v55, 0xffff0000, v49
	v_lshlrev_b32_e32 v56, 16, v50
	v_and_b32_e32 v57, 0xffff0000, v50
	v_lshlrev_b32_e32 v58, 16, v51
	v_and_b32_e32 v59, 0xffff0000, v51
	v_add_f32_e32 v8, v8, v52
	v_add_f32_e32 v9, v9, v53
	v_add_f32_e32 v10, v10, v54
	v_add_f32_e32 v11, v11, v55
	v_add_f32_e32 v12, v12, v56
	v_add_f32_e32 v13, v13, v57
	v_add_f32_e32 v14, v14, v58
	v_add_f32_e32 v15, v15, v59
	v_cvt_pk_bf16_f32 v48, v8, v9
	v_cvt_pk_bf16_f32 v49, v10, v11
	v_cvt_pk_bf16_f32 v50, v12, v13
	v_cvt_pk_bf16_f32 v51, v14, v15
	global_store_dwordx4 v63, v[48:51], s[100:101]
	s_branch .LBB0_956
.Lmerge_first:
	ds_read_b128 v[20:23], v62 offset:0
	ds_read_b128 v[24:27], v62 offset:4352
	ds_read_b128 v[28:31], v62 offset:8704
	ds_read_b128 v[32:35], v62 offset:13056
	ds_read_b128 v[36:39], v62 offset:17408
	ds_read_b128 v[40:43], v62 offset:21760
	ds_read_b128 v[44:47], v62 offset:26112
	ds_read_b128 v[48:51], v62 offset:30464
	s_waitcnt lgkmcnt(7)
	global_store_dwordx4 v63, v[20:23], s[100:101]
	s_add_u32 s100, s100, 0x8000
	s_addc_u32 s101, s101, 0
	s_waitcnt lgkmcnt(6)
	global_store_dwordx4 v63, v[24:27], s[100:101]
	s_add_u32 s100, s100, 0x8000
	s_addc_u32 s101, s101, 0
	s_waitcnt lgkmcnt(5)
	global_store_dwordx4 v63, v[28:31], s[100:101]
	s_add_u32 s100, s100, 0x8000
	s_addc_u32 s101, s101, 0
	s_waitcnt lgkmcnt(4)
	global_store_dwordx4 v63, v[32:35], s[100:101]
	s_add_u32 s100, s100, 0x8000
	s_addc_u32 s101, s101, 0
	s_waitcnt lgkmcnt(3)
	global_store_dwordx4 v63, v[36:39], s[100:101]
	s_add_u32 s100, s100, 0x8000
	s_addc_u32 s101, s101, 0
	s_waitcnt lgkmcnt(2)
	global_store_dwordx4 v63, v[40:43], s[100:101]
	s_add_u32 s100, s100, 0x8000
	s_addc_u32 s101, s101, 0
	s_waitcnt lgkmcnt(1)
	global_store_dwordx4 v63, v[44:47], s[100:101]
	s_add_u32 s100, s100, 0x8000
	s_addc_u32 s101, s101, 0
	s_waitcnt lgkmcnt(0)
	global_store_dwordx4 v63, v[48:51], s[100:101]
	s_branch .LBB0_956

; __device__ void phase_out(PRef p, int l, const bf16* M, const float* xl, const float* xc, bf16* sA, bf16* sB) {
;     ...
;     int b = rt / 18;
;     bool isctx = (rt % 18) < 2;
;     const float* gate = p.MOD + ((size_t)l * 17 + (isctx ? 16 : b)) * 3072 + 2048;
;     stage_tile<2>(acc, sA);
;     TILE_CHUNKS(2, sA, {
;       int R = rt * 128 + trow;
;       int col = ct * 128 + tcol;
;       int tp = R % TPB;
;       const float* xin;
;       float* dstp;
;       if (isctx) {
;         xin = xc + ((size_t)b * 256 + tp) * 1024 + col;
;         dstp = p.XC + ((size_t)b * 256 + tp) * 1024 + col;
;       } else {
;         xin = xl + ((size_t)b * 2048 + (tp - 256)) * 1024 + col;
;         dstp = p.out + ((size_t)b * 2048 + (tp - 256)) * 1024 + col;
;       }
;       f32x4v x0 = *(const f32x4v*)xin, x1 = *(const f32x4v*)(xin + 4);
;       f32x4v g0 = *(const f32x4v*)(gate + col), g1 = *(const f32x4v*)(gate + col + 4);
;       f32x4v o0, o1;
;       o0.x = x0.x + g0.x * __uint_as_float(cv[0] << 16);
;       o0.y = x0.y + g0.y * __uint_as_float(cv[0] & 0xffff0000u);
;       o0.z = x0.z + g0.z * __uint_as_float(cv[1] << 16);
;       o0.w = x0.w + g0.w * __uint_as_float(cv[1] & 0xffff0000u);
;       o1.x = x1.x + g1.x * __uint_as_float(cv[2] << 16);
;       o1.y = x1.y + g1.y * __uint_as_float(cv[2] & 0xffff0000u);
;       o1.z = x1.z + g1.z * __uint_as_float(cv[3] << 16);
;       o1.w = x1.w + g1.w * __uint_as_float(cv[3] & 0xffff0000u);
;       *(f32x4v*)dstp = o0;
;       *(f32x4v*)(dstp + 4) = o1;
;     })
.LBB0_1089:
	v_mov_b32_e32 v0, v196
	s_nop 5
	v_cvt_pk_bf16_f32 v52, v52, v53
	v_lshrrev_b32_e32 v1, 1, v0
	v_and_b32_e32 v2, 31, v0
	v_and_or_b32 v1, v1, s75, v2
	v_and_b32_e32 v2, 64, v0
	v_lshrrev_b32_e32 v0, 2, v0
	v_and_b32_e32 v0, 8, v0
	v_lshl_or_b32 v0, v2, 1, v0
	v_mad_u64_u32 v[0:1], s[14:15], v1, s52, v[0:1]
	v_cvt_pk_bf16_f32 v53, v54, v55
	v_cvt_pk_bf16_f32 v54, v56, v57
	v_cvt_pk_bf16_f32 v55, v58, v59
	v_cvt_pk_bf16_f32 v36, v36, v37
	v_cvt_pk_bf16_f32 v37, v38, v39
	v_cvt_pk_bf16_f32 v38, v40, v41
	v_cvt_pk_bf16_f32 v39, v42, v43
	s_barrier
	ds_write2_b64 v0, v[52:53], v[54:55] offset1:2
	v_cvt_pk_bf16_f32 v52, v60, v61
	v_cvt_pk_bf16_f32 v53, v62, v63
	v_cvt_pk_bf16_f32 v54, v64, v65
	v_cvt_pk_bf16_f32 v55, v66, v67
	ds_write2_b64 v0, v[36:37], v[38:39] offset0:8 offset1:10
	v_cvt_pk_bf16_f32 v36, v44, v45
	v_cvt_pk_bf16_f32 v37, v46, v47
	v_cvt_pk_bf16_f32 v38, v48, v49
	v_cvt_pk_bf16_f32 v39, v50, v51
	v_cvt_pk_bf16_f32 v20, v20, v21
	v_cvt_pk_bf16_f32 v21, v22, v23
	v_cvt_pk_bf16_f32 v22, v24, v25
	v_cvt_pk_bf16_f32 v23, v26, v27
	v_add_u32_e32 v2, 0x2000, v0
	ds_write2_b64 v0, v[52:53], v[54:55] offset0:4 offset1:6
	ds_write2_b64 v0, v[36:37], v[38:39] offset0:12 offset1:14
	ds_write2_b64 v2, v[20:21], v[22:23] offset0:64 offset1:66
	v_cvt_pk_bf16_f32 v0, v28, v29
	v_cvt_pk_bf16_f32 v1, v30, v31
	v_cvt_pk_bf16_f32 v20, v32, v33
	v_cvt_pk_bf16_f32 v21, v34, v35
	ds_write2_b64 v2, v[0:1], v[20:21] offset0:68 offset1:70
	v_cvt_pk_bf16_f32 v0, v4, v5
	v_cvt_pk_bf16_f32 v1, v6, v7
	v_cvt_pk_bf16_f32 v4, v8, v9
	v_cvt_pk_bf16_f32 v5, v10, v11
	ds_write2_b64 v2, v[0:1], v[4:5] offset0:72 offset1:74
	v_cvt_pk_bf16_f32 v0, v12, v13
	v_cvt_pk_bf16_f32 v1, v14, v15
	v_cvt_pk_bf16_f32 v4, v16, v17
	v_cvt_pk_bf16_f32 v5, v18, v19
	ds_write2_b64 v2, v[0:1], v[4:5] offset0:76 offset1:78
	v_mov_b32_e32 v2, v196
	s_waitcnt lgkmcnt(0)
	s_barrier
	s_lshl_b32 s36, s4, 7
	s_mul_i32 s14, s18, 0x900
	s_sub_u32 s14, s36, s14
	s_andn2_b64 vcc, exec, s[24:25]
	s_cbranch_vccnz .Lout_ctx
	s_sub_u32 s14, s14, 0x100
	s_lshl_b32 s15, s18, 11
	s_mov_b64 s[30:31], s[40:41]
	s_mov_b64 s[26:27], s[10:11]
	s_branch .Lout_ptr
.Lout_ctx:
	s_lshl_b32 s15, s18, 8
	s_mov_b64 s[30:31], s[42:43]
	s_mov_b64 s[26:27], s[0:1]
.Lout_ptr:
	s_add_u32 s14, s14, s15
	s_lshl_b32 s35, s20, 7
	s_lshl_b32 s16, s14, 12
	s_lshl_b32 s14, s35, 2
	s_add_u32 s16, s16, s14
	s_add_u32 s98, s30, s16
	s_addc_u32 s99, s31, 0
	s_add_u32 s100, s26, s16
	s_addc_u32 s101, s27, 0
	s_and_b64 s[22:23], s[22:23], exec
	s_cselect_b32 s18, 16, s18
	s_ashr_i32 s19, s18, 31
	s_add_u32 s18, s8, s18
	s_addc_u32 s19, s9, s19
	s_mulk_i32 s19, 0x3000
	s_mul_hi_u32 s21, s18, 0x3000
	s_add_i32 s21, s21, s19
	s_mulk_i32 s18, 0x3000
	s_add_u32 s18, s76, s18
	s_addc_u32 s19, s77, s21
	s_add_u32 s18, s18, 0x2000
	s_addc_u32 s19, s19, 0
	s_add_u32 s18, s18, s14
	s_addc_u32 s19, s19, 0
	v_lshrrev_b32_e32 v92, 4, v196
	v_and_b32_e32 v93, 15, v196
	v_mul_lo_u32 v94, v92, s52
	v_lshl_add_u32 v94, v93, 4, v94
	v_lshlrev_b32_e32 v95, 12, v92
	v_lshl_add_u32 v95, v93, 5, v95
	v_lshlrev_b32_e32 v93, 5, v93
	global_load_dwordx4 v[84:87], v93, s[18:19]
	global_load_dwordx4 v[88:91], v93, s[18:19] offset:16
	global_load_dwordx4 v[20:23], v95, s[98:99]
	global_load_dwordx4 v[24:27], v95, s[98:99] offset:16
	s_add_u32 s98, s98, 0x10000
	s_addc_u32 s99, s99, 0
	global_load_dwordx4 v[28:31], v95, s[98:99]
	global_load_dwordx4 v[32:35], v95, s[98:99] offset:16
	s_add_u32 s98, s98, 0x10000
	s_addc_u32 s99, s99, 0
	global_load_dwordx4 v[36:39], v95, s[98:99]
	global_load_dwordx4 v[40:43], v95, s[98:99] offset:16
	s_add_u32 s98, s98, 0x10000
	s_addc_u32 s99, s99, 0
	global_load_dwordx4 v[44:47], v95, s[98:99]
	global_load_dwordx4 v[48:51], v95, s[98:99] offset:16
	s_add_u32 s98, s98, 0x10000
	s_addc_u32 s99, s99, 0
	global_load_dwordx4 v[52:55], v95, s[98:99]
	global_load_dwordx4 v[56:59], v95, s[98:99] offset:16
	s_add_u32 s98, s98, 0x10000
	s_addc_u32 s99, s99, 0
	global_load_dwordx4 v[60:63], v95, s[98:99]
	global_load_dwordx4 v[64:67], v95, s[98:99] offset:16
	s_add_u32 s98, s98, 0x10000
	s_addc_u32 s99, s99, 0
	global_load_dwordx4 v[68:71], v95, s[98:99]
	global_load_dwordx4 v[72:75], v95, s[98:99] offset:16
	s_add_u32 s98, s98, 0x10000
	s_addc_u32 s99, s99, 0
	global_load_dwordx4 v[76:79], v95, s[98:99]
	global_load_dwordx4 v[80:83], v95, s[98:99] offset:16
	ds_read_b128 v[4:7], v94 offset:0
	s_waitcnt vmcnt(14) lgkmcnt(0)
	v_lshlrev_b32_e32 v8, 16, v4
	v_and_b32_e32 v9, 0xffff0000, v4
	v_lshlrev_b32_e32 v10, 16, v5
	v_and_b32_e32 v11, 0xffff0000, v5
	v_lshlrev_b32_e32 v12, 16, v6
	v_and_b32_e32 v13, 0xffff0000, v6
	v_lshlrev_b32_e32 v14, 16, v7
	v_and_b32_e32 v15, 0xffff0000, v7
	v_fmac_f32_e32 v20, v84, v8
	v_fmac_f32_e32 v21, v85, v9
	v_fmac_f32_e32 v22, v86, v10
	v_fmac_f32_e32 v23, v87, v11
	v_fmac_f32_e32 v24, v88, v12
	v_fmac_f32_e32 v25, v89, v13
	v_fmac_f32_e32 v26, v90, v14
	v_fmac_f32_e32 v27, v91, v15
	global_store_dwordx4 v95, v[20:23], s[100:101]
	global_store_dwordx4 v95, v[24:27], s[100:101] offset:16
	s_add_u32 s100, s100, 0x10000
	s_addc_u32 s101, s101, 0
	ds_read_b128 v[4:7], v94 offset:4352
	s_waitcnt vmcnt(14) lgkmcnt(0)
; __device__ void phase_out(PRef p, int l, const bf16* M, const float* xl, const float* xc, bf16* sA, bf16* sB) {
;     ...
;     TILE_CHUNKS(2, sA, {
;       int R = rt * 128 + trow;
;       int col = ct * 128 + tcol;
;       int tp = R % TPB;
;       const float* xin;
;       float* dstp;
;       if (isctx) {
;         xin = xc + ((size_t)b * 256 + tp) * 1024 + col;
;         dstp = p.XC + ((size_t)b * 256 + tp) * 1024 + col;
;       } else {
;         xin = xl + ((size_t)b * 2048 + (tp - 256)) * 1024 + col;
;         dstp = p.out + ((size_t)b * 2048 + (tp - 256)) * 1024 + col;
;       }
;       f32x4v x0 = *(const f32x4v*)xin, x1 = *(const f32x4v*)(xin + 4);
;       f32x4v g0 = *(const f32x4v*)(gate + col), g1 = *(const f32x4v*)(gate + col + 4);
;       f32x4v o0, o1;
;       o0.x = x0.x + g0.x * __uint_as_float(cv[0] << 16);
;       o0.y = x0.y + g0.y * __uint_as_float(cv[0] & 0xffff0000u);
;       o0.z = x0.z + g0.z * __uint_as_float(cv[1] << 16);
;       o0.w = x0.w + g0.w * __uint_as_float(cv[1] & 0xffff0000u);
;       o1.x = x1.x + g1.x * __uint_as_float(cv[2] << 16);
;       o1.y = x1.y + g1.y * __uint_as_float(cv[2] & 0xffff0000u);
;       o1.z = x1.z + g1.z * __uint_as_float(cv[3] << 16);
;       o1.w = x1.w + g1.w * __uint_as_float(cv[3] & 0xffff0000u);
;       *(f32x4v*)dstp = o0;
;       *(f32x4v*)(dstp + 4) = o1;
;     })
	v_lshlrev_b32_e32 v8, 16, v4
	v_and_b32_e32 v9, 0xffff0000, v4
	v_lshlrev_b32_e32 v10, 16, v5
	v_and_b32_e32 v11, 0xffff0000, v5
	v_lshlrev_b32_e32 v12, 16, v6
	v_and_b32_e32 v13, 0xffff0000, v6
	v_lshlrev_b32_e32 v14, 16, v7
	v_and_b32_e32 v15, 0xffff0000, v7
	v_fmac_f32_e32 v28, v84, v8
	v_fmac_f32_e32 v29, v85, v9
	v_fmac_f32_e32 v30, v86, v10
	v_fmac_f32_e32 v31, v87, v11
	v_fmac_f32_e32 v32, v88, v12
	v_fmac_f32_e32 v33, v89, v13
	v_fmac_f32_e32 v34, v90, v14
	v_fmac_f32_e32 v35, v91, v15
	global_store_dwordx4 v95, v[28:31], s[100:101]
	global_store_dwordx4 v95, v[32:35], s[100:101] offset:16
	s_add_u32 s100, s100, 0x10000
	s_addc_u32 s101, s101, 0
	ds_read_b128 v[4:7], v94 offset:8704
	s_waitcnt vmcnt(14) lgkmcnt(0)
	v_lshlrev_b32_e32 v8, 16, v4
	v_and_b32_e32 v9, 0xffff0000, v4
	v_lshlrev_b32_e32 v10, 16, v5
	v_and_b32_e32 v11, 0xffff0000, v5
	v_lshlrev_b32_e32 v12, 16, v6
	v_and_b32_e32 v13, 0xffff0000, v6
	v_lshlrev_b32_e32 v14, 16, v7
	v_and_b32_e32 v15, 0xffff0000, v7
	v_fmac_f32_e32 v36, v84, v8
	v_fmac_f32_e32 v37, v85, v9
	v_fmac_f32_e32 v38, v86, v10
	v_fmac_f32_e32 v39, v87, v11
	v_fmac_f32_e32 v40, v88, v12
	v_fmac_f32_e32 v41, v89, v13
	v_fmac_f32_e32 v42, v90, v14
	v_fmac_f32_e32 v43, v91, v15
	global_store_dwordx4 v95, v[36:39], s[100:101]
	global_store_dwordx4 v95, v[40:43], s[100:101] offset:16
	s_add_u32 s100, s100, 0x10000
	s_addc_u32 s101, s101, 0
	ds_read_b128 v[4:7], v94 offset:13056
	s_waitcnt vmcnt(14) lgkmcnt(0)
	v_lshlrev_b32_e32 v8, 16, v4
	v_and_b32_e32 v9, 0xffff0000, v4
	v_lshlrev_b32_e32 v10, 16, v5
	v_and_b32_e32 v11, 0xffff0000, v5
	v_lshlrev_b32_e32 v12, 16, v6
	v_and_b32_e32 v13, 0xffff0000, v6
	v_lshlrev_b32_e32 v14, 16, v7
	v_and_b32_e32 v15, 0xffff0000, v7
	v_fmac_f32_e32 v44, v84, v8
	v_fmac_f32_e32 v45, v85, v9
	v_fmac_f32_e32 v46, v86, v10
	v_fmac_f32_e32 v47, v87, v11
	v_fmac_f32_e32 v48, v88, v12
	v_fmac_f32_e32 v49, v89, v13
	v_fmac_f32_e32 v50, v90, v14
	v_fmac_f32_e32 v51, v91, v15
	global_store_dwordx4 v95, v[44:47], s[100:101]
	global_store_dwordx4 v95, v[48:51], s[100:101] offset:16
	s_add_u32 s100, s100, 0x10000
	s_addc_u32 s101, s101, 0
	ds_read_b128 v[4:7], v94 offset:17408
	s_waitcnt vmcnt(14) lgkmcnt(0)
	v_lshlrev_b32_e32 v8, 16, v4
	v_and_b32_e32 v9, 0xffff0000, v4
	v_lshlrev_b32_e32 v10, 16, v5
	v_and_b32_e32 v11, 0xffff0000, v5
	v_lshlrev_b32_e32 v12, 16, v6
	v_and_b32_e32 v13, 0xffff0000, v6
	v_lshlrev_b32_e32 v14, 16, v7
	v_and_b32_e32 v15, 0xffff0000, v7
	v_fmac_f32_e32 v52, v84, v8
	v_fmac_f32_e32 v53, v85, v9
	v_fmac_f32_e32 v54, v86, v10
	v_fmac_f32_e32 v55, v87, v11
	v_fmac_f32_e32 v56, v88, v12
	v_fmac_f32_e32 v57, v89, v13
	v_fmac_f32_e32 v58, v90, v14
	v_fmac_f32_e32 v59, v91, v15
	global_store_dwordx4 v95, v[52:55], s[100:101]
	global_store_dwordx4 v95, v[56:59], s[100:101] offset:16
	s_add_u32 s100, s100, 0x10000
	s_addc_u32 s101, s101, 0
	ds_read_b128 v[4:7], v94 offset:21760
	s_waitcnt vmcnt(14) lgkmcnt(0)
	v_lshlrev_b32_e32 v8, 16, v4
	v_and_b32_e32 v9, 0xffff0000, v4
	v_lshlrev_b32_e32 v10, 16, v5
	v_and_b32_e32 v11, 0xffff0000, v5
	v_lshlrev_b32_e32 v12, 16, v6
	v_and_b32_e32 v13, 0xffff0000, v6
	v_lshlrev_b32_e32 v14, 16, v7
	v_and_b32_e32 v15, 0xffff0000, v7
	v_fmac_f32_e32 v60, v84, v8
	v_fmac_f32_e32 v61, v85, v9
	v_fmac_f32_e32 v62, v86, v10
	v_fmac_f32_e32 v63, v87, v11
	v_fmac_f32_e32 v64, v88, v12
	v_fmac_f32_e32 v65, v89, v13
	v_fmac_f32_e32 v66, v90, v14
	v_fmac_f32_e32 v67, v91, v15
	global_store_dwordx4 v95, v[60:63], s[100:101]
	global_store_dwordx4 v95, v[64:67], s[100:101] offset:16
	s_add_u32 s100, s100, 0x10000
	s_addc_u32 s101, s101, 0
	ds_read_b128 v[4:7], v94 offset:26112
	s_waitcnt vmcnt(14) lgkmcnt(0)
	v_lshlrev_b32_e32 v8, 16, v4
	v_and_b32_e32 v9, 0xffff0000, v4
	v_lshlrev_b32_e32 v10, 16, v5
	v_and_b32_e32 v11, 0xffff0000, v5
	v_lshlrev_b32_e32 v12, 16, v6
	v_and_b32_e32 v13, 0xffff0000, v6
	v_lshlrev_b32_e32 v14, 16, v7
	v_and_b32_e32 v15, 0xffff0000, v7
	v_fmac_f32_e32 v68, v84, v8
	v_fmac_f32_e32 v69, v85, v9
	v_fmac_f32_e32 v70, v86, v10
	v_fmac_f32_e32 v71, v87, v11
	v_fmac_f32_e32 v72, v88, v12
	v_fmac_f32_e32 v73, v89, v13
	v_fmac_f32_e32 v74, v90, v14
	v_fmac_f32_e32 v75, v91, v15
	global_store_dwordx4 v95, v[68:71], s[100:101]
	global_store_dwordx4 v95, v[72:75], s[100:101] offset:16
	s_add_u32 s100, s100, 0x10000
	s_addc_u32 s101, s101, 0
	ds_read_b128 v[4:7], v94 offset:30464
	s_waitcnt vmcnt(14) lgkmcnt(0)
	v_lshlrev_b32_e32 v8, 16, v4
	v_and_b32_e32 v9, 0xffff0000, v4
	v_lshlrev_b32_e32 v10, 16, v5
	v_and_b32_e32 v11, 0xffff0000, v5
	v_lshlrev_b32_e32 v12, 16, v6
	v_and_b32_e32 v13, 0xffff0000, v6
	v_lshlrev_b32_e32 v14, 16, v7
	v_and_b32_e32 v15, 0xffff0000, v7
	v_fmac_f32_e32 v76, v84, v8
	v_fmac_f32_e32 v77, v85, v9
	v_fmac_f32_e32 v78, v86, v10
	v_fmac_f32_e32 v79, v87, v11
	v_fmac_f32_e32 v80, v88, v12
	v_fmac_f32_e32 v81, v89, v13
	v_fmac_f32_e32 v82, v90, v14
	v_fmac_f32_e32 v83, v91, v15
	global_store_dwordx4 v95, v[76:79], s[100:101]
	global_store_dwordx4 v95, v[80:83], s[100:101] offset:16
	s_branch .LBB0_1081
